# c14: elementwise in-proj tiles stage and flush in two 64-row halves through the upper LDS stage, so the next tile's first LDS-DMA stage is issued right after the K-loop and lands during the epilogue
# baseline (speedup 1.0000x reference)
; __device__ void gemm1_phase(const Params& p, int l, int hb, unsigned char* smem) {
;     const bf16_t* H = (const bf16_t*)(p.ws + WS_H);
;     const bf16_t* Wt = (const bf16_t*)(p.ws + WS_WIN) + (size_t)l * NP * 1024;
;     const float* ropec = (const float*)(p.ws + WS_ROPE); const float* ropes = ropec + 2048;
;     constexpr int NT = 34, NTILES = 64 * NT, GRP = 8 * NT;
;     for (int t = blockIdx.x; t < NTILES; t += gridDim.x) {
.LBB0_250:
	s_or_b64 exec, exec, s[36:37]
	v_readlane_b32 s16, v253, 17
	v_readlane_b32 s17, v253, 18
	s_waitcnt lgkmcnt(0)
	s_barrier
	v_readlane_b32 s18, v253, 19
	v_readlane_b32 s19, v253, 20
	s_mov_b64 s[16:17], s[18:19]
	v_readlane_b32 s20, v253, 21
	v_readlane_b32 s21, v253, 22
	s_mov_b64 s[16:17], s[20:21]
	v_readlane_b32 s22, v253, 23
	v_readlane_b32 s23, v253, 24
	s_mov_b64 s[16:17], s[22:23]
	v_readlane_b32 s24, v253, 25
	v_readlane_b32 s25, v253, 26
	s_mov_b64 s[16:17], s[24:25]
	v_readlane_b32 s26, v253, 27
	v_readlane_b32 s27, v253, 28
	s_mov_b64 s[16:17], s[26:27]
	v_readlane_b32 s28, v253, 29
	v_readlane_b32 s29, v253, 30
	v_readlane_b32 s30, v253, 31
	v_readlane_b32 s31, v253, 32
	s_mov_b64 s[36:37], s[28:29]
	s_mov_b64 s[40:41], s[30:31]
	v_readlane_b32 s16, v253, 33
	v_readlane_b32 s17, v253, 34
	v_readlane_b32 s18, v253, 35
	v_readlane_b32 s19, v253, 36
	v_readlane_b32 s20, v253, 37
	v_readlane_b32 s21, v253, 38
	v_readlane_b32 s22, v253, 39
	v_readlane_b32 s23, v253, 40
	s_mov_b64 s[42:43], s[16:17]
	s_mov_b64 s[44:45], s[18:19]
	s_mov_b64 s[46:47], s[20:21]
	s_mov_b64 s[16:17], s[22:23]
	v_readlane_b32 s24, v253, 41
	v_readlane_b32 s25, v253, 42
	s_mov_b64 s[16:17], s[24:25]
	v_readlane_b32 s26, v253, 43
	v_readlane_b32 s27, v253, 44
	s_mov_b64 s[16:17], s[26:27]
	v_readlane_b32 s28, v253, 45
	v_readlane_b32 s29, v253, 46
	s_mov_b64 s[16:17], s[28:29]
	v_readlane_b32 s30, v253, 47
	v_readlane_b32 s31, v253, 48
	s_mov_b64 s[38:39], s[30:31]
	v_readlane_b32 s16, v253, 1
	v_readlane_b32 s17, v253, 2
	v_readlane_b32 s18, v253, 3
	v_readlane_b32 s19, v253, 4
	s_mov_b64 s[16:17], s[18:19]
	v_readlane_b32 s20, v253, 5
	v_readlane_b32 s21, v253, 6
	s_mov_b64 s[16:17], s[20:21]
	v_readlane_b32 s22, v253, 7
	v_readlane_b32 s23, v253, 8
	s_mov_b64 s[16:17], s[22:23]
	v_readlane_b32 s24, v253, 9
	v_readlane_b32 s25, v253, 10
	s_mov_b64 s[16:17], s[24:25]
	v_readlane_b32 s26, v253, 11
	v_readlane_b32 s27, v253, 12
	s_mov_b64 s[16:17], s[26:27]
	v_readlane_b32 s28, v253, 13
	v_readlane_b32 s29, v253, 14
	s_mov_b64 s[16:17], s[28:29]
	v_readlane_b32 s30, v253, 15
	v_readlane_b32 s16, v254, 45
	v_readlane_b32 s31, v253, 16
	v_readlane_b32 s17, v254, 46
	s_mov_b64 s[48:49], s[30:31]
	s_andn2_b64 vcc, exec, s[16:17]
	s_cbranch_vccnz .LBB0_573
	s_add_u32 s92, s48, 0x3000000
	s_addc_u32 s93, s49, 0
	v_readlane_b32 s16, v255, 37
	v_readlane_b32 s17, v255, 38
	s_add_u32 s94, s48, s16
	s_addc_u32 s95, s49, s17
	s_add_u32 s26, s48, 0x2b20000
	s_addc_u32 s27, s49, 0
	s_add_u32 s52, s48, 0x2b22000
	s_addc_u32 s53, s49, 0
	s_add_u32 s28, s48, 0xc800000
	s_addc_u32 s29, s49, 0
	s_add_u32 s30, s48, 0xc000000
	s_addc_u32 s31, s49, 0
	s_add_u32 s16, s48, 0x6800000
	s_addc_u32 s17, s49, 0
	v_writelane_b32 v255, s16, 48
	v_readlane_b32 s60, v253, 0
	s_nop 0
	v_writelane_b32 v255, s17, 49
	s_add_u32 s16, s48, 0x6400000
	s_addc_u32 s17, s49, 0
	v_writelane_b32 v255, s16, 50
	s_nop 1
	v_writelane_b32 v255, s17, 51
	s_nop 0
	v_readlane_b32 s16, v255, 39
	v_readlane_b32 s17, v255, 40
	s_add_u32 s25, s36, s16
	s_addc_u32 s51, s37, s17
	s_add_u32 s16, s48, 0x2d00000
	s_addc_u32 s17, s49, 0
	v_writelane_b32 v255, s16, 52
	s_nop 1
	v_writelane_b32 v255, s17, 53
	s_nop 0
	v_readlane_b32 s16, v255, 28
	v_readlane_b32 s17, v255, 29
	s_lshl_b64 s[16:17], s[16:17], 2
	s_add_u32 s16, s38, s16
	s_addc_u32 s17, s39, s17
	v_writelane_b32 v255, s16, 54
	s_add_u32 s66, s48, 0xa800000
	s_addc_u32 s67, s49, 0
	v_writelane_b32 v255, s17, 55
	s_add_u32 s96, s48, 0x3000080
	v_readlane_b32 s16, v255, 33
	s_addc_u32 s97, s49, 0
	s_mul_i32 s9, s16, 0x1100000
	s_add_u32 s9, s48, s9
	s_mul_hi_u32 s11, s16, 0x1100000
	s_addc_u32 s11, s49, s11
	v_readlane_b32 s17, v255, 34
	s_add_u32 s64, s9, 0x80
	v_writelane_b32 v255, s66, 56
	s_addc_u32 s65, s11, 0
	s_nop 0
	v_writelane_b32 v255, s67, 57
	s_mov_b32 s98, 0
	s_branch .LBB0_254

; #define LDSAS __attribute__((address_space(3)))
; #define G_ISSUE(kt, st) do { G_ISSUE1(kt, st, 0); G_ISSUE1(kt, st, 1); G_ISSUE1(kt, st, 2); G_ISSUE1(kt, st, 3); } while (0)
; template <bool LOWREG = false>
; __device__ __forceinline__ void gemm_core(const bf16_t* __restrict__ A, int lda, const bf16_t* __restrict__ Bt, int ldb, int K, f32x4 (&acc)[8][4], unsigned char* smem, int tid) {
;     asm volatile("" : "+v"(tid));
;     const int lane = tid & 63, w = __builtin_amdgcn_readfirstlane(tid >> 6), wm = w >> 2, wn = w & 3, idx = lane & 15, kq = lane >> 4;
;     unsigned offA[4], offB[4];
; #pragma unroll
;     for (int j = 0; j < 4; ++j) { const int row = (j * 8 + w) * 8 + (lane >> 3), c = (lane & 7) ^ ((row >> 1) & 7);
;         offA[j] = (unsigned)(row * lda + c * 8) * 2u; offB[j] = (unsigned)(row * ldb + c * 8) * 2u; }
; #pragma unroll
;     for (int mi = 0; mi < 8; ++mi)
; #pragma unroll
;         for (int ni = 0; ni < 4; ++ni) acc[mi][ni] = (f32x4){0.f, 0.f, 0.f, 0.f};
;     LDSAS unsigned char* lds = (LDSAS unsigned char*)smem;
;     ...
;     const int nk = K >> 6;
;     G_ISSUE(0, 0);
;     asm volatile("s_waitcnt vmcnt(0)" ::: "memory");
;     __syncthreads();
;     const int swz = (idx >> 1) & 7;
;     const int aoff = (wm * 128 + idx) * 128, boff = G_AB + (wn * 64 + idx) * 128;
.LBB0_254:
	s_mul_hi_i32 s9, s60, 0x78787879
	s_lshr_b32 s11, s9, 31
	s_ashr_i32 s9, s9, 7
	s_add_i32 s9, s9, s11
	s_mul_i32 s11, s9, 0x110
	s_sub_i32 s11, s60, s11
	s_and_b32 s12, s11, 7
	s_mul_i32 s12, s12, 34
	s_ashr_i32 s11, s11, 3
	s_add_i32 s12, s12, s11
	s_lshl_b32 s11, s12, 8
	s_lshl_b32 s9, s9, 11
	s_and_b32 s11, s11, 0x700
	s_or_b32 s56, s11, s9
	s_lshl_b32 s11, s12, 5
	s_ashr_i32 s57, s56, 31
	s_and_b32 s36, s11, 0xffffff00
	s_lshl_b64 s[16:17], s[56:57], 11
	s_add_u32 s18, s92, s16
	s_addc_u32 s19, s93, s17
	s_ashr_i32 s37, s36, 31
	s_lshl_b64 s[20:21], s[36:37], 11
	v_mov_b32_e32 v0, v210
	s_add_u32 s22, s94, s20
	s_addc_u32 s23, s95, s21
	v_readfirstlane_b32 s12, v0
	s_ashr_i32 s24, s12, 6
	s_and_b32 s101, s24, 3
	s_cmp_lg_u32 s101, 0
	s_cselect_b32 s101, 1, 0
	s_cmp_eq_u32 s36, 0x2100
	s_cselect_b32 s101, s101, 0
	v_bfe_u32 v2, v0, 3, 3
	v_lshl_or_b32 v3, s24, 3, v2
	v_lshrrev_b32_e32 v4, 1, v3
	v_xor_b32_e32 v4, v4, v0
	v_lshlrev_b32_e32 v4, 4, v4
	s_lshl_b32 s9, s24, 10
	v_and_b32_e32 v4, 0x70, v4
	s_add_i32 s9, s9, 0
	v_lshl_or_b32 v3, v3, 11, v4
	v_add_u32_e32 v5, 0x20000, v3
	v_add_u32_e32 v6, 0x40000, v3
	v_add_u32_e32 v7, 0x60000, v3
	s_cmp_lg_u32 s98, 0
	s_cbranch_scc1 .Lg1_dma_skip
	s_mov_b32 m0, s9
	s_nop 0
	global_load_lds_dwordx4 v3, s[18:19]
	s_add_i32 m0, s9, 0x8000
	s_nop 0
	global_load_lds_dwordx4 v3, s[22:23]
	s_add_i32 m0, s9, 0x2000
	s_nop 0
	global_load_lds_dwordx4 v5, s[18:19]
	s_add_i32 m0, s9, 0xa000
	s_nop 0
	global_load_lds_dwordx4 v5, s[22:23]
	s_add_i32 m0, s9, 0x4000
	s_nop 0
	global_load_lds_dwordx4 v6, s[18:19]
	s_add_i32 m0, s9, 0xc000
	s_nop 0
	global_load_lds_dwordx4 v6, s[22:23]
	s_add_i32 m0, s9, 0x6000
	s_nop 0
	global_load_lds_dwordx4 v7, s[18:19]
	s_add_i32 m0, s9, 0xe000
	s_nop 0
	global_load_lds_dwordx4 v7, s[22:23]
.Lg1_dma_skip:
	v_and_b32_e32 v1, 15, v0
	v_bfe_u32 v8, v0, 4, 2
	v_lshrrev_b32_e32 v3, 1, v0
	v_bfe_u32 v0, v0, 1, 3
	s_lshr_b32 s18, s12, 1
	s_and_b32 s18, s18, 0x1ffff80
	s_and_b32 s12, s12, 0xc0
	v_or_b32_e32 v5, s18, v1
	v_or_b32_e32 v1, s12, v1
	s_lshl_b32 s12, s24, 14
	s_add_u32 s16, s96, s16
	v_lshlrev_b32_e32 v149, 7, v5
	v_bitop3_b32 v0, v8, v0, 4 bitop3:0x36
	v_lshlrev_b32_e32 v5, 11, v2
	s_addc_u32 s17, s97, s17
	s_add_i32 s18, s12, 0x20000
	v_lshlrev_b32_e32 v147, 7, v1
	v_bitop3_b32 v1, v8, v3, 7 bitop3:0x78
	v_lshlrev_b32_e32 v146, 4, v0
	v_or3_b32 v80, s12, v5, v4
	v_or3_b32 v0, s18, v5, v4
	s_add_i32 s18, s12, 0x40000
	s_add_i32 s12, s12, 0x60000
	v_lshlrev_b32_e32 v148, 4, v1
	v_mov_b32_e32 v1, v81
	v_or3_b32 v2, s18, v5, v4
	v_mov_b32_e32 v3, v81
	v_or3_b32 v4, s12, v5, v4
	v_mov_b32_e32 v5, v81
	v_lshl_add_u64 v[130:131], s[16:17], 0, v[80:81]
	v_lshl_add_u64 v[132:133], s[16:17], 0, v[0:1]
	v_lshl_add_u64 v[134:135], s[16:17], 0, v[2:3]
	v_lshl_add_u64 v[136:137], s[16:17], 0, v[4:5]
	s_add_u32 s16, s64, s20
	s_addc_u32 s17, s65, s21
	s_cmp_lg_u32 s98, 0
	s_cbranch_scc1 .Lg1_hw16
	s_waitcnt vmcnt(0)
	s_branch .Lg1_hwd
.Lg1_hw16:
	s_waitcnt vmcnt(16)
.Lg1_hwd:
	s_mov_b32 s98, 0
	v_lshl_add_u64 v[140:141], s[16:17], 0, v[0:1]
	v_mov_b32_e32 v0, 0
	v_lshl_add_u64 v[138:139], s[16:17], 0, v[80:81]
	v_lshl_add_u64 v[142:143], s[16:17], 0, v[2:3]
	v_lshl_add_u64 v[144:145], s[16:17], 0, v[4:5]
	s_mov_b32 s12, 0
	s_mov_b64 s[38:39], 0
	v_mov_b32_e32 v1, v0
	v_mov_b32_e32 v2, v0
	v_mov_b32_e32 v3, v0
	v_mov_b32_e32 v4, v0
	v_mov_b32_e32 v5, v0
	v_mov_b32_e32 v6, v0
	v_mov_b32_e32 v7, v0
	v_mov_b32_e32 v8, v0
	v_mov_b32_e32 v9, v0
	v_mov_b32_e32 v10, v0
	v_mov_b32_e32 v11, v0
	v_mov_b32_e32 v12, v0
	v_mov_b32_e32 v13, v0
	v_mov_b32_e32 v14, v0
	v_mov_b32_e32 v15, v0
	v_mov_b32_e32 v16, v0
	v_mov_b32_e32 v17, v0
	v_mov_b32_e32 v18, v0
	v_mov_b32_e32 v19, v0
	v_mov_b32_e32 v20, v0
	v_mov_b32_e32 v21, v0
	v_mov_b32_e32 v22, v0
	v_mov_b32_e32 v23, v0
	v_mov_b32_e32 v24, v0
	v_mov_b32_e32 v25, v0
	v_mov_b32_e32 v26, v0
	v_mov_b32_e32 v27, v0
	v_mov_b32_e32 v28, v0
	v_mov_b32_e32 v29, v0
	v_mov_b32_e32 v30, v0
	v_mov_b32_e32 v31, v0
	v_mov_b32_e32 v32, v0
	v_mov_b32_e32 v33, v0
	v_mov_b32_e32 v34, v0
	v_mov_b32_e32 v35, v0
	v_mov_b32_e32 v36, v0
	v_mov_b32_e32 v37, v0
	v_mov_b32_e32 v38, v0
	v_mov_b32_e32 v39, v0
	v_mov_b32_e32 v40, v0
	v_mov_b32_e32 v41, v0
	v_mov_b32_e32 v42, v0
	v_mov_b32_e32 v43, v0
	v_mov_b32_e32 v44, v0
	v_mov_b32_e32 v45, v0
	v_mov_b32_e32 v46, v0
	v_mov_b32_e32 v47, v0
	v_mov_b32_e32 v48, v0
	v_mov_b32_e32 v49, v0
	v_mov_b32_e32 v50, v0
	v_mov_b32_e32 v51, v0
	v_mov_b32_e32 v52, v0
	v_mov_b32_e32 v53, v0
	v_mov_b32_e32 v54, v0
	v_mov_b32_e32 v55, v0
	v_mov_b32_e32 v56, v0
	v_mov_b32_e32 v57, v0
	v_mov_b32_e32 v58, v0
	v_mov_b32_e32 v59, v0
	v_mov_b32_e32 v60, v0
	v_mov_b32_e32 v61, v0
	v_mov_b32_e32 v62, v0
	v_mov_b32_e32 v63, v0
	v_mov_b32_e32 v64, v0
	v_mov_b32_e32 v65, v0
	v_mov_b32_e32 v66, v0
	v_mov_b32_e32 v67, v0
	v_mov_b32_e32 v68, v0
	v_mov_b32_e32 v69, v0
	v_mov_b32_e32 v70, v0
	v_mov_b32_e32 v71, v0
	v_mov_b32_e32 v72, v0
	v_mov_b32_e32 v73, v0
	v_mov_b32_e32 v74, v0
	v_mov_b32_e32 v75, v0
	v_mov_b32_e32 v76, v0
	v_mov_b32_e32 v77, v0
	v_mov_b32_e32 v78, v0
	v_mov_b32_e32 v79, v0
	v_mov_b32_e32 v82, v0
	v_mov_b32_e32 v83, v0
	v_mov_b32_e32 v84, v0
	v_mov_b32_e32 v85, v0
	v_mov_b32_e32 v86, v0
	v_mov_b32_e32 v87, v0
	v_mov_b32_e32 v88, v0
	v_mov_b32_e32 v89, v0
	v_mov_b32_e32 v90, v0
	v_mov_b32_e32 v91, v0
	v_mov_b32_e32 v92, v0
	v_mov_b32_e32 v93, v0
	v_mov_b32_e32 v94, v0
	v_mov_b32_e32 v95, v0
	v_mov_b32_e32 v96, v0
	v_mov_b32_e32 v97, v0
	v_mov_b32_e32 v98, v0
	v_mov_b32_e32 v99, v0
	v_mov_b32_e32 v100, v0
	v_mov_b32_e32 v101, v0
	v_mov_b32_e32 v102, v0
	v_mov_b32_e32 v103, v0
	v_mov_b32_e32 v104, v0
	v_mov_b32_e32 v105, v0
	v_mov_b32_e32 v106, v0
	v_mov_b32_e32 v107, v0
	v_mov_b32_e32 v108, v0
	v_mov_b32_e32 v109, v0
	v_mov_b32_e32 v110, v0
	v_mov_b32_e32 v111, v0
	v_mov_b32_e32 v112, v0
	v_mov_b32_e32 v113, v0
	v_mov_b32_e32 v114, v0
	v_mov_b32_e32 v115, v0
	v_mov_b32_e32 v116, v0
	v_mov_b32_e32 v117, v0
	v_mov_b32_e32 v118, v0
	v_mov_b32_e32 v119, v0
	v_mov_b32_e32 v120, v0
	v_mov_b32_e32 v121, v0
	v_mov_b32_e32 v122, v0
	v_mov_b32_e32 v123, v0
	v_mov_b32_e32 v124, v0
	v_mov_b32_e32 v125, v0
	v_mov_b32_e32 v126, v0
	v_mov_b32_e32 v127, v0
	v_mov_b32_e32 v128, v0
	v_mov_b32_e32 v129, v0
	s_waitcnt lgkmcnt(0)
	s_barrier

; __device__ __forceinline__ float siluf(float v) { return v * __builtin_amdgcn_rcpf(1.f + __builtin_amdgcn_exp2f(-1.4426950408889634f * v)); }
; __device__ __forceinline__ float sigmf(float v) { return __builtin_amdgcn_rcpf(1.f + __builtin_amdgcn_exp2f(-1.4426950408889634f * v)); }
; __device__ void gemm1_phase(const Params& p, int l, int hb, unsigned char* smem) {
;     ...
;             int mode;
;             if (cw < 768) { dbase = (bf16_t*)(p.ws + WS_VA); dpitch = 128; dc0 = cw - 640; mode = 0; }
;             else if (cw < 1280) { dbase = (bf16_t*)(p.ws + WS_GA); dpitch = 512; dc0 = cw - 768; mode = 1; }
;             else if (cw < 3840) { dbase = (bf16_t*)(p.ws + WS_GB); dpitch = 256; dc0 = cw - 3584; mode = 1; }
;             else if (cw < 4864) { dbase = (bf16_t*)(p.ws + WS_XBC); dpitch = 1024; dc0 = cw - 3840; mode = 0; }
;             else if (cw < 5376) { dbase = (bf16_t*)(p.ws + WS_ZS); dpitch = 512; dc0 = cw - 4864; mode = 1; }
;             else { dbase = (bf16_t*)(p.ws + WS_MG); dpitch = 3072; dc0 = cw - 5376; mode = 2; }
;             const float* bg = p.b_gate + l * 3072 + dc0 + lc;
; #pragma unroll
;             for (int mi = 0; mi < 8; ++mi) {
; #pragma unroll
;                 for (int ni = 0; ni < 4; ++ni) {
;                     f32x4 v = acc[mi][ni];
;                     if (mode == 1) { v.x = siluf(v.x); v.y = siluf(v.y); v.z = siluf(v.z); v.w = siluf(v.w); }
;                     else if (mode == 2) { const f32x4 bb = *(const f32x4*)(bg + ni * 16); v.x = sigmf(v.x + bb.x); v.y = sigmf(v.y + bb.y); v.z = sigmf(v.z + bb.z); v.w = sigmf(v.w + bb.w); }
;                     G1_STG(mi, ni, v);
;                 }
;             }
;         }
;     ...
;         if (dbase) {
;             const int ch = lane & 7;
; #pragma unroll
;             for (int j = 0; j < 16; ++j) {
;                 const int rl = 8 * j + (lane >> 3), row = m0 + wm * 128 + rl;
;                 const u32x4 v = *(const u32x4*)(wl + rl * 128 + ((ch ^ (rl & 7)) * 16));
;                 size_t drow = (size_t)row;
;                 if (dsh >= 0) { const int bl = row >> 13, tt = row & (SEQ - 1); drow = (size_t)(bl * 3 + dg) * SEQ + (size_t)((tt & ((1 << dsh) - 1)) * (SEQ >> dsh) + (tt >> dsh)); }
;                 *(u32x4*)(dbase + drow * dpitch + dc0 + ch * 8) = v;
;             }
;         }
.LBB0_271:
	s_add_i32 s58, s9, s54
	s_ashr_i32 s59, s58, 31
	s_xor_b64 s[62:63], s[38:39], -1
	s_lshl_b64 s[16:17], s[58:59], 2
	s_add_u32 s16, s25, s16
	s_addc_u32 s17, s51, s17
	v_lshlrev_b32_e32 v80, 2, v157
	v_lshl_add_u64 v[130:131], s[16:17], 0, v[80:81]
	global_load_dwordx4 v[160:163], v[130:131], off
	global_load_dwordx4 v[164:167], v[130:131], off offset:64
	global_load_dwordx4 v[168:171], v[130:131], off offset:128
	global_load_dwordx4 v[172:175], v[130:131], off offset:192
	s_and_b32 s100, s54, 0xffffff00
	s_cmpk_eq_i32 s100, 0x200
	s_cselect_b32 s100, 1, 0
	s_add_i32 s98, s60, s8
	s_cmpk_lt_i32 s98, 0x880
	s_cbranch_scc0 .Lg1e_nopre
	s_cmp_lg_u32 s100, 0
	s_cbranch_scc1 .Lg1e_nopre
	s_mul_hi_i32 s16, s98, 0x78787879
	s_lshr_b32 s17, s16, 31
	s_ashr_i32 s16, s16, 7
	s_add_i32 s16, s16, s17
	s_mul_i32 s17, s16, 0x110
	s_sub_i32 s17, s98, s17
	s_and_b32 s20, s17, 7
	s_mul_i32 s20, s20, 34
	s_ashr_i32 s17, s17, 3
	s_add_i32 s20, s20, s17
	s_lshl_b32 s17, s20, 8
	s_lshl_b32 s16, s16, 11
	s_and_b32 s17, s17, 0x700
	s_or_b32 s16, s17, s16
	s_lshl_b32 s20, s20, 5
	s_and_b32 s20, s20, 0xffffff00
	s_ashr_i32 s17, s16, 31
	s_lshl_b64 s[16:17], s[16:17], 11
	s_add_u32 s18, s92, s16
	s_addc_u32 s19, s93, s17
	s_ashr_i32 s21, s20, 31
	s_lshl_b64 s[20:21], s[20:21], 11
	s_add_u32 s22, s94, s20
	s_addc_u32 s23, s95, s21
	v_readfirstlane_b32 s99, v210
	s_ashr_i32 s99, s99, 6
	v_bfe_u32 v140, v210, 3, 3
	v_lshl_or_b32 v140, s99, 3, v140
	v_lshrrev_b32_e32 v141, 1, v140
	v_xor_b32_e32 v141, v141, v210
	v_lshlrev_b32_e32 v141, 4, v141
	v_and_b32_e32 v141, 0x70, v141
	v_lshl_or_b32 v140, v140, 11, v141
	v_add_u32_e32 v141, 0x20000, v140
	v_add_u32_e32 v142, 0x40000, v140
	v_add_u32_e32 v143, 0x60000, v140
	s_lshl_b32 s99, s99, 10
	s_mov_b32 m0, s99
	s_nop 0
	global_load_lds_dwordx4 v140, s[18:19]
	s_add_i32 m0, s99, 0x8000
	s_nop 0
	global_load_lds_dwordx4 v140, s[22:23]
	s_add_i32 m0, s99, 0x2000
	s_nop 0
	global_load_lds_dwordx4 v141, s[18:19]
	s_add_i32 m0, s99, 0xa000
	s_nop 0
	global_load_lds_dwordx4 v141, s[22:23]
	s_add_i32 m0, s99, 0x4000
	s_nop 0
	global_load_lds_dwordx4 v142, s[18:19]
	s_add_i32 m0, s99, 0xc000
	s_nop 0
	global_load_lds_dwordx4 v142, s[22:23]
	s_add_i32 m0, s99, 0x6000
	s_nop 0
	global_load_lds_dwordx4 v143, s[18:19]
	s_add_i32 m0, s99, 0xe000
	s_nop 0
	global_load_lds_dwordx4 v143, s[22:23]
	s_mov_b32 s98, 1
	s_branch .Lg1e_predone
.Lg1e_nopre:
	s_mov_b32 s98, 0
.Lg1e_predone:
	v_readlane_b32 s66, v255, 56
	v_readlane_b32 s67, v255, 57
	s_lshr_b32 s99, s61, 1
	s_add_i32 s99, s99, 0x10000
	s_cmp_lg_u32 s100, 0
	s_cselect_b32 s99, s61, s99
	v_lshlrev_b32_e32 v130, 7, v231
	v_and_b32_e32 v131, 1, v156
	v_lshl_add_u32 v130, v131, 3, v130
	v_add_u32_e32 v130, s99, v130
	v_lshrrev_b32_e32 v131, 1, v156
	v_and_b32_e32 v132, 7, v231
	v_or_b32_e32 v133, 0, v131
	v_xor_b32_e32 v133, v133, v132
	v_lshl_add_u32 v136, v133, 4, v130
	v_or_b32_e32 v133, 2, v131
	v_xor_b32_e32 v133, v133, v132
	v_lshl_add_u32 v137, v133, 4, v130
	v_or_b32_e32 v133, 4, v131
	v_xor_b32_e32 v133, v133, v132
	v_lshl_add_u32 v138, v133, 4, v130
	v_or_b32_e32 v133, 6, v131
	v_xor_b32_e32 v133, v133, v132
	v_lshl_add_u32 v139, v133, 4, v130
	v_lshrrev_b32_e32 v146, 3, v230
	v_and_b32_e32 v147, 7, v181
	v_xor_b32_e32 v144, v147, v146
	v_lshl_add_u32 v144, v144, 4, s99
	v_lshl_add_u32 v144, v146, 7, v144
	s_lshl_b32 s12, s57, 7
	s_add_i32 s12, s12, s56
	v_add_u32_e32 v145, s12, v146
	v_mul_lo_u32 v145, v145, s88
	v_add_u32_e32 v145, s58, v145
	v_lshlrev_b32_e32 v145, 1, v145
	v_lshl_add_u32 v145, v147, 4, v145
	s_lshl_b32 s100, s88, 4
	s_and_b64 vcc, exec, s[36:37]
	s_cbranch_vccnz .Lg1e_sig
	s_and_b64 vcc, exec, s[38:39]
	s_cbranch_vccnz .Lg1e_silu
	v_cvt_pk_bf16_f32 v126, v126, v127
	v_cvt_pk_bf16_f32 v127, v128, v129
	ds_write_b64 v136, v[126:127]
	v_cvt_pk_bf16_f32 v122, v122, v123
	v_cvt_pk_bf16_f32 v123, v124, v125
	ds_write_b64 v137, v[122:123]
	v_cvt_pk_bf16_f32 v118, v118, v119
	v_cvt_pk_bf16_f32 v119, v120, v121
	ds_write_b64 v138, v[118:119]
	v_cvt_pk_bf16_f32 v114, v114, v115
	v_cvt_pk_bf16_f32 v115, v116, v117
	ds_write_b64 v139, v[114:115]
	v_cvt_pk_bf16_f32 v110, v110, v111
	v_cvt_pk_bf16_f32 v111, v112, v113
	ds_write_b64 v136, v[110:111] offset:2048
	v_cvt_pk_bf16_f32 v106, v106, v107
	v_cvt_pk_bf16_f32 v107, v108, v109
	ds_write_b64 v137, v[106:107] offset:2048
	v_cvt_pk_bf16_f32 v102, v102, v103
	v_cvt_pk_bf16_f32 v103, v104, v105
	ds_write_b64 v138, v[102:103] offset:2048
	v_cvt_pk_bf16_f32 v98, v98, v99
	v_cvt_pk_bf16_f32 v99, v100, v101
	ds_write_b64 v139, v[98:99] offset:2048
	v_cvt_pk_bf16_f32 v94, v94, v95
	v_cvt_pk_bf16_f32 v95, v96, v97
	ds_write_b64 v136, v[94:95] offset:4096
	v_cvt_pk_bf16_f32 v90, v90, v91
	v_cvt_pk_bf16_f32 v91, v92, v93
	ds_write_b64 v137, v[90:91] offset:4096
	v_cvt_pk_bf16_f32 v86, v86, v87
	v_cvt_pk_bf16_f32 v87, v88, v89
	ds_write_b64 v138, v[86:87] offset:4096
	v_cvt_pk_bf16_f32 v82, v82, v83
	v_cvt_pk_bf16_f32 v83, v84, v85
	ds_write_b64 v139, v[82:83] offset:4096
	v_cvt_pk_bf16_f32 v76, v76, v77
	v_cvt_pk_bf16_f32 v77, v78, v79
	ds_write_b64 v136, v[76:77] offset:6144
	v_cvt_pk_bf16_f32 v72, v72, v73
	v_cvt_pk_bf16_f32 v73, v74, v75
	ds_write_b64 v137, v[72:73] offset:6144
	v_cvt_pk_bf16_f32 v68, v68, v69
	v_cvt_pk_bf16_f32 v69, v70, v71
	ds_write_b64 v138, v[68:69] offset:6144
	v_cvt_pk_bf16_f32 v64, v64, v65
	v_cvt_pk_bf16_f32 v65, v66, v67
	ds_write_b64 v139, v[64:65] offset:6144
	ds_read_b128 v[98:101], v144
	ds_read_b128 v[102:105], v144 offset:1024
	ds_read_b128 v[106:109], v144 offset:2048
	ds_read_b128 v[110:113], v144 offset:3072
	ds_read_b128 v[114:117], v144 offset:4096
	ds_read_b128 v[118:121], v144 offset:5120
	ds_read_b128 v[122:125], v144 offset:6144
	ds_read_b128 v[126:129], v144 offset:7168
	s_waitcnt lgkmcnt(7)
; __device__ __forceinline__ float siluf(float v) { return v * __builtin_amdgcn_rcpf(1.f + __builtin_amdgcn_exp2f(-1.4426950408889634f * v)); }
; __device__ __forceinline__ float sigmf(float v) { return __builtin_amdgcn_rcpf(1.f + __builtin_amdgcn_exp2f(-1.4426950408889634f * v)); }
; __device__ void gemm1_phase(const Params& p, int l, int hb, unsigned char* smem) {
;     ...
;             int mode;
;             if (cw < 768) { dbase = (bf16_t*)(p.ws + WS_VA); dpitch = 128; dc0 = cw - 640; mode = 0; }
;             else if (cw < 1280) { dbase = (bf16_t*)(p.ws + WS_GA); dpitch = 512; dc0 = cw - 768; mode = 1; }
;             else if (cw < 3840) { dbase = (bf16_t*)(p.ws + WS_GB); dpitch = 256; dc0 = cw - 3584; mode = 1; }
;             else if (cw < 4864) { dbase = (bf16_t*)(p.ws + WS_XBC); dpitch = 1024; dc0 = cw - 3840; mode = 0; }
;             else if (cw < 5376) { dbase = (bf16_t*)(p.ws + WS_ZS); dpitch = 512; dc0 = cw - 4864; mode = 1; }
;             else { dbase = (bf16_t*)(p.ws + WS_MG); dpitch = 3072; dc0 = cw - 5376; mode = 2; }
;             const float* bg = p.b_gate + l * 3072 + dc0 + lc;
; #pragma unroll
;             for (int mi = 0; mi < 8; ++mi) {
; #pragma unroll
;                 for (int ni = 0; ni < 4; ++ni) {
;                     f32x4 v = acc[mi][ni];
;                     if (mode == 1) { v.x = siluf(v.x); v.y = siluf(v.y); v.z = siluf(v.z); v.w = siluf(v.w); }
;                     else if (mode == 2) { const f32x4 bb = *(const f32x4*)(bg + ni * 16); v.x = sigmf(v.x + bb.x); v.y = sigmf(v.y + bb.y); v.z = sigmf(v.z + bb.z); v.w = sigmf(v.w + bb.w); }
;                     G1_STG(mi, ni, v);
;                 }
;             }
;         }
;     ...
;         if (dbase) {
;             const int ch = lane & 7;
; #pragma unroll
;             for (int j = 0; j < 16; ++j) {
;                 const int rl = 8 * j + (lane >> 3), row = m0 + wm * 128 + rl;
;                 const u32x4 v = *(const u32x4*)(wl + rl * 128 + ((ch ^ (rl & 7)) * 16));
;                 size_t drow = (size_t)row;
;                 if (dsh >= 0) { const int bl = row >> 13, tt = row & (SEQ - 1); drow = (size_t)(bl * 3 + dg) * SEQ + (size_t)((tt & ((1 << dsh) - 1)) * (SEQ >> dsh) + (tt >> dsh)); }
;                 *(u32x4*)(dbase + drow * dpitch + dc0 + ch * 8) = v;
;             }
;         }
	global_store_dwordx4 v145, v[98:101], s[90:91]
	v_add_u32_e32 v145, s100, v145
	s_waitcnt lgkmcnt(6)
	global_store_dwordx4 v145, v[102:105], s[90:91]
	v_add_u32_e32 v145, s100, v145
	s_waitcnt lgkmcnt(5)
	global_store_dwordx4 v145, v[106:109], s[90:91]
	v_add_u32_e32 v145, s100, v145
	s_waitcnt lgkmcnt(4)
	global_store_dwordx4 v145, v[110:113], s[90:91]
	v_add_u32_e32 v145, s100, v145
	s_waitcnt lgkmcnt(3)
	global_store_dwordx4 v145, v[114:117], s[90:91]
	v_add_u32_e32 v145, s100, v145
	s_waitcnt lgkmcnt(2)
	global_store_dwordx4 v145, v[118:121], s[90:91]
	v_add_u32_e32 v145, s100, v145
	s_waitcnt lgkmcnt(1)
	global_store_dwordx4 v145, v[122:125], s[90:91]
	v_add_u32_e32 v145, s100, v145
	s_waitcnt lgkmcnt(0)
	global_store_dwordx4 v145, v[126:129], s[90:91]
	v_add_u32_e32 v145, s100, v145
	v_cvt_pk_bf16_f32 v60, v60, v61
	v_cvt_pk_bf16_f32 v61, v62, v63
	ds_write_b64 v136, v[60:61]
	v_cvt_pk_bf16_f32 v56, v56, v57
	v_cvt_pk_bf16_f32 v57, v58, v59
	ds_write_b64 v137, v[56:57]
	v_cvt_pk_bf16_f32 v52, v52, v53
	v_cvt_pk_bf16_f32 v53, v54, v55
	ds_write_b64 v138, v[52:53]
	v_cvt_pk_bf16_f32 v48, v48, v49
	v_cvt_pk_bf16_f32 v49, v50, v51
	ds_write_b64 v139, v[48:49]
	v_cvt_pk_bf16_f32 v44, v44, v45
	v_cvt_pk_bf16_f32 v45, v46, v47
	ds_write_b64 v136, v[44:45] offset:2048
	v_cvt_pk_bf16_f32 v40, v40, v41
	v_cvt_pk_bf16_f32 v41, v42, v43
	ds_write_b64 v137, v[40:41] offset:2048
	v_cvt_pk_bf16_f32 v36, v36, v37
	v_cvt_pk_bf16_f32 v37, v38, v39
	ds_write_b64 v138, v[36:37] offset:2048
	v_cvt_pk_bf16_f32 v32, v32, v33
	v_cvt_pk_bf16_f32 v33, v34, v35
	ds_write_b64 v139, v[32:33] offset:2048
	v_cvt_pk_bf16_f32 v28, v28, v29
	v_cvt_pk_bf16_f32 v29, v30, v31
	ds_write_b64 v136, v[28:29] offset:4096
	v_cvt_pk_bf16_f32 v24, v24, v25
	v_cvt_pk_bf16_f32 v25, v26, v27
	ds_write_b64 v137, v[24:25] offset:4096
	v_cvt_pk_bf16_f32 v20, v20, v21
	v_cvt_pk_bf16_f32 v21, v22, v23
	ds_write_b64 v138, v[20:21] offset:4096
	v_cvt_pk_bf16_f32 v16, v16, v17
	v_cvt_pk_bf16_f32 v17, v18, v19
	ds_write_b64 v139, v[16:17] offset:4096
	v_cvt_pk_bf16_f32 v12, v12, v13
	v_cvt_pk_bf16_f32 v13, v14, v15
	ds_write_b64 v136, v[12:13] offset:6144
	v_cvt_pk_bf16_f32 v8, v8, v9
	v_cvt_pk_bf16_f32 v9, v10, v11
	ds_write_b64 v137, v[8:9] offset:6144
	v_cvt_pk_bf16_f32 v4, v4, v5
	v_cvt_pk_bf16_f32 v5, v6, v7
	ds_write_b64 v138, v[4:5] offset:6144
	v_cvt_pk_bf16_f32 v0, v0, v1
	v_cvt_pk_bf16_f32 v1, v2, v3
	ds_write_b64 v139, v[0:1] offset:6144
	ds_read_b128 v[0:3], v144
	ds_read_b128 v[4:7], v144 offset:1024
	ds_read_b128 v[8:11], v144 offset:2048
	ds_read_b128 v[12:15], v144 offset:3072
	ds_read_b128 v[16:19], v144 offset:4096
	ds_read_b128 v[20:23], v144 offset:5120
	ds_read_b128 v[24:27], v144 offset:6144
	ds_read_b128 v[28:31], v144 offset:7168
	s_waitcnt lgkmcnt(7)
	global_store_dwordx4 v145, v[0:3], s[90:91]
	v_add_u32_e32 v145, s100, v145
	s_waitcnt lgkmcnt(6)
	global_store_dwordx4 v145, v[4:7], s[90:91]
	v_add_u32_e32 v145, s100, v145
	s_waitcnt lgkmcnt(5)
	global_store_dwordx4 v145, v[8:11], s[90:91]
	v_add_u32_e32 v145, s100, v145
	s_waitcnt lgkmcnt(4)
	global_store_dwordx4 v145, v[12:15], s[90:91]
	v_add_u32_e32 v145, s100, v145
	s_waitcnt lgkmcnt(3)
	global_store_dwordx4 v145, v[16:19], s[90:91]
	v_add_u32_e32 v145, s100, v145
	s_waitcnt lgkmcnt(2)
	global_store_dwordx4 v145, v[20:23], s[90:91]
	v_add_u32_e32 v145, s100, v145
	s_waitcnt lgkmcnt(1)
	global_store_dwordx4 v145, v[24:27], s[90:91]
	v_add_u32_e32 v145, s100, v145
	s_waitcnt lgkmcnt(0)
	global_store_dwordx4 v145, v[28:31], s[90:91]
	v_add_u32_e32 v145, s100, v145
	s_branch .LBB0_253
.Lg1e_silu:
	v_mul_f32_e32 v130, 0xbfb8aa3b, v126
	v_mul_f32_e32 v131, 0xbfb8aa3b, v127
	v_mul_f32_e32 v132, 0xbfb8aa3b, v128
	v_mul_f32_e32 v133, 0xbfb8aa3b, v129
	v_exp_f32_e32 v130, v130
	v_exp_f32_e32 v131, v131
	v_exp_f32_e32 v132, v132
	v_exp_f32_e32 v133, v133
	v_add_f32_e32 v130, 1.0, v130
	v_add_f32_e32 v131, 1.0, v131
	v_add_f32_e32 v132, 1.0, v132
	v_add_f32_e32 v133, 1.0, v133
	v_rcp_f32_e32 v130, v130
	v_rcp_f32_e32 v131, v131
	v_rcp_f32_e32 v132, v132
	v_rcp_f32_e32 v133, v133
	v_pk_mul_f32 v[126:127], v[126:127], v[130:131]
	v_pk_mul_f32 v[128:129], v[128:129], v[132:133]
	v_cvt_pk_bf16_f32 v126, v126, v127
	v_cvt_pk_bf16_f32 v127, v128, v129
	ds_write_b64 v136, v[126:127]
	v_mul_f32_e32 v130, 0xbfb8aa3b, v122
	v_mul_f32_e32 v131, 0xbfb8aa3b, v123
	v_mul_f32_e32 v132, 0xbfb8aa3b, v124
	v_mul_f32_e32 v133, 0xbfb8aa3b, v125
	v_exp_f32_e32 v130, v130
	v_exp_f32_e32 v131, v131
	v_exp_f32_e32 v132, v132
	v_exp_f32_e32 v133, v133
	v_add_f32_e32 v130, 1.0, v130
	v_add_f32_e32 v131, 1.0, v131
	v_add_f32_e32 v132, 1.0, v132
	v_add_f32_e32 v133, 1.0, v133
	v_rcp_f32_e32 v130, v130
	v_rcp_f32_e32 v131, v131
	v_rcp_f32_e32 v132, v132
	v_rcp_f32_e32 v133, v133
	v_pk_mul_f32 v[122:123], v[122:123], v[130:131]
	v_pk_mul_f32 v[124:125], v[124:125], v[132:133]
	v_cvt_pk_bf16_f32 v122, v122, v123
	v_cvt_pk_bf16_f32 v123, v124, v125
	ds_write_b64 v137, v[122:123]
	v_mul_f32_e32 v130, 0xbfb8aa3b, v118
	v_mul_f32_e32 v131, 0xbfb8aa3b, v119
	v_mul_f32_e32 v132, 0xbfb8aa3b, v120
	v_mul_f32_e32 v133, 0xbfb8aa3b, v121
	v_exp_f32_e32 v130, v130
	v_exp_f32_e32 v131, v131
	v_exp_f32_e32 v132, v132
	v_exp_f32_e32 v133, v133
	v_add_f32_e32 v130, 1.0, v130
	v_add_f32_e32 v131, 1.0, v131
	v_add_f32_e32 v132, 1.0, v132
	v_add_f32_e32 v133, 1.0, v133
	v_rcp_f32_e32 v130, v130
	v_rcp_f32_e32 v131, v131
	v_rcp_f32_e32 v132, v132
	v_rcp_f32_e32 v133, v133
	v_pk_mul_f32 v[118:119], v[118:119], v[130:131]
	v_pk_mul_f32 v[120:121], v[120:121], v[132:133]
	v_cvt_pk_bf16_f32 v118, v118, v119
	v_cvt_pk_bf16_f32 v119, v120, v121
	ds_write_b64 v138, v[118:119]
; __device__ __forceinline__ float siluf(float v) { return v * __builtin_amdgcn_rcpf(1.f + __builtin_amdgcn_exp2f(-1.4426950408889634f * v)); }
; __device__ __forceinline__ float sigmf(float v) { return __builtin_amdgcn_rcpf(1.f + __builtin_amdgcn_exp2f(-1.4426950408889634f * v)); }
; #define G1_STG(mi_, ni_, v_) do { const int r_ = (mi_) * 16 + idx; const f32x4 t_ = (v_); u32x2 pk_; pk_.x = pk2(t_.x, t_.y); pk_.y = pk2(t_.z, t_.w); \
;         *(u32x2*)(wl + r_ * 128 + ((((ni_) * 2 + (kq >> 1)) ^ (r_ & 7)) * 16) + (kq & 1) * 8) = pk_; } while (0)
; __device__ void gemm1_phase(const Params& p, int l, int hb, unsigned char* smem) {
;     ...
; #pragma unroll
;             for (int mi = 0; mi < 8; ++mi) {
; #pragma unroll
;                 for (int ni = 0; ni < 4; ++ni) {
;                     f32x4 v = acc[mi][ni];
;                     if (mode == 1) { v.x = siluf(v.x); v.y = siluf(v.y); v.z = siluf(v.z); v.w = siluf(v.w); }
;                     else if (mode == 2) { const f32x4 bb = *(const f32x4*)(bg + ni * 16); v.x = sigmf(v.x + bb.x); v.y = sigmf(v.y + bb.y); v.z = sigmf(v.z + bb.z); v.w = sigmf(v.w + bb.w); }
;                     G1_STG(mi, ni, v);
;                 }
	v_mul_f32_e32 v130, 0xbfb8aa3b, v114
	v_mul_f32_e32 v131, 0xbfb8aa3b, v115
	v_mul_f32_e32 v132, 0xbfb8aa3b, v116
	v_mul_f32_e32 v133, 0xbfb8aa3b, v117
	v_exp_f32_e32 v130, v130
	v_exp_f32_e32 v131, v131
	v_exp_f32_e32 v132, v132
	v_exp_f32_e32 v133, v133
	v_add_f32_e32 v130, 1.0, v130
	v_add_f32_e32 v131, 1.0, v131
	v_add_f32_e32 v132, 1.0, v132
	v_add_f32_e32 v133, 1.0, v133
	v_rcp_f32_e32 v130, v130
	v_rcp_f32_e32 v131, v131
	v_rcp_f32_e32 v132, v132
	v_rcp_f32_e32 v133, v133
	v_pk_mul_f32 v[114:115], v[114:115], v[130:131]
	v_pk_mul_f32 v[116:117], v[116:117], v[132:133]
	v_cvt_pk_bf16_f32 v114, v114, v115
	v_cvt_pk_bf16_f32 v115, v116, v117
	ds_write_b64 v139, v[114:115]
	v_mul_f32_e32 v130, 0xbfb8aa3b, v110
	v_mul_f32_e32 v131, 0xbfb8aa3b, v111
	v_mul_f32_e32 v132, 0xbfb8aa3b, v112
	v_mul_f32_e32 v133, 0xbfb8aa3b, v113
	v_exp_f32_e32 v130, v130
	v_exp_f32_e32 v131, v131
	v_exp_f32_e32 v132, v132
	v_exp_f32_e32 v133, v133
	v_add_f32_e32 v130, 1.0, v130
	v_add_f32_e32 v131, 1.0, v131
	v_add_f32_e32 v132, 1.0, v132
	v_add_f32_e32 v133, 1.0, v133
	v_rcp_f32_e32 v130, v130
	v_rcp_f32_e32 v131, v131
	v_rcp_f32_e32 v132, v132
	v_rcp_f32_e32 v133, v133
	v_pk_mul_f32 v[110:111], v[110:111], v[130:131]
	v_pk_mul_f32 v[112:113], v[112:113], v[132:133]
	v_cvt_pk_bf16_f32 v110, v110, v111
	v_cvt_pk_bf16_f32 v111, v112, v113
	ds_write_b64 v136, v[110:111] offset:2048
	v_mul_f32_e32 v130, 0xbfb8aa3b, v106
	v_mul_f32_e32 v131, 0xbfb8aa3b, v107
	v_mul_f32_e32 v132, 0xbfb8aa3b, v108
	v_mul_f32_e32 v133, 0xbfb8aa3b, v109
	v_exp_f32_e32 v130, v130
	v_exp_f32_e32 v131, v131
	v_exp_f32_e32 v132, v132
	v_exp_f32_e32 v133, v133
	v_add_f32_e32 v130, 1.0, v130
	v_add_f32_e32 v131, 1.0, v131
	v_add_f32_e32 v132, 1.0, v132
	v_add_f32_e32 v133, 1.0, v133
	v_rcp_f32_e32 v130, v130
	v_rcp_f32_e32 v131, v131
	v_rcp_f32_e32 v132, v132
	v_rcp_f32_e32 v133, v133
	v_pk_mul_f32 v[106:107], v[106:107], v[130:131]
	v_pk_mul_f32 v[108:109], v[108:109], v[132:133]
	v_cvt_pk_bf16_f32 v106, v106, v107
	v_cvt_pk_bf16_f32 v107, v108, v109
	ds_write_b64 v137, v[106:107] offset:2048
	v_mul_f32_e32 v130, 0xbfb8aa3b, v102
	v_mul_f32_e32 v131, 0xbfb8aa3b, v103
	v_mul_f32_e32 v132, 0xbfb8aa3b, v104
	v_mul_f32_e32 v133, 0xbfb8aa3b, v105
	v_exp_f32_e32 v130, v130
	v_exp_f32_e32 v131, v131
	v_exp_f32_e32 v132, v132
	v_exp_f32_e32 v133, v133
	v_add_f32_e32 v130, 1.0, v130
	v_add_f32_e32 v131, 1.0, v131
	v_add_f32_e32 v132, 1.0, v132
	v_add_f32_e32 v133, 1.0, v133
	v_rcp_f32_e32 v130, v130
	v_rcp_f32_e32 v131, v131
	v_rcp_f32_e32 v132, v132
	v_rcp_f32_e32 v133, v133
	v_pk_mul_f32 v[102:103], v[102:103], v[130:131]
	v_pk_mul_f32 v[104:105], v[104:105], v[132:133]
	v_cvt_pk_bf16_f32 v102, v102, v103
	v_cvt_pk_bf16_f32 v103, v104, v105
	ds_write_b64 v138, v[102:103] offset:2048
	v_mul_f32_e32 v130, 0xbfb8aa3b, v98
	v_mul_f32_e32 v131, 0xbfb8aa3b, v99
	v_mul_f32_e32 v132, 0xbfb8aa3b, v100
	v_mul_f32_e32 v133, 0xbfb8aa3b, v101
	v_exp_f32_e32 v130, v130
	v_exp_f32_e32 v131, v131
	v_exp_f32_e32 v132, v132
	v_exp_f32_e32 v133, v133
	v_add_f32_e32 v130, 1.0, v130
	v_add_f32_e32 v131, 1.0, v131
	v_add_f32_e32 v132, 1.0, v132
	v_add_f32_e32 v133, 1.0, v133
	v_rcp_f32_e32 v130, v130
	v_rcp_f32_e32 v131, v131
	v_rcp_f32_e32 v132, v132
	v_rcp_f32_e32 v133, v133
	v_pk_mul_f32 v[98:99], v[98:99], v[130:131]
	v_pk_mul_f32 v[100:101], v[100:101], v[132:133]
	v_cvt_pk_bf16_f32 v98, v98, v99
	v_cvt_pk_bf16_f32 v99, v100, v101
	ds_write_b64 v139, v[98:99] offset:2048
	v_mul_f32_e32 v130, 0xbfb8aa3b, v94
	v_mul_f32_e32 v131, 0xbfb8aa3b, v95
	v_mul_f32_e32 v132, 0xbfb8aa3b, v96
	v_mul_f32_e32 v133, 0xbfb8aa3b, v97
	v_exp_f32_e32 v130, v130
	v_exp_f32_e32 v131, v131
	v_exp_f32_e32 v132, v132
	v_exp_f32_e32 v133, v133
	v_add_f32_e32 v130, 1.0, v130
	v_add_f32_e32 v131, 1.0, v131
	v_add_f32_e32 v132, 1.0, v132
	v_add_f32_e32 v133, 1.0, v133
	v_rcp_f32_e32 v130, v130
	v_rcp_f32_e32 v131, v131
	v_rcp_f32_e32 v132, v132
	v_rcp_f32_e32 v133, v133
	v_pk_mul_f32 v[94:95], v[94:95], v[130:131]
	v_pk_mul_f32 v[96:97], v[96:97], v[132:133]
	v_cvt_pk_bf16_f32 v94, v94, v95
	v_cvt_pk_bf16_f32 v95, v96, v97
	ds_write_b64 v136, v[94:95] offset:4096
	v_mul_f32_e32 v130, 0xbfb8aa3b, v90
	v_mul_f32_e32 v131, 0xbfb8aa3b, v91
	v_mul_f32_e32 v132, 0xbfb8aa3b, v92
	v_mul_f32_e32 v133, 0xbfb8aa3b, v93
	v_exp_f32_e32 v130, v130
	v_exp_f32_e32 v131, v131
	v_exp_f32_e32 v132, v132
	v_exp_f32_e32 v133, v133
	v_add_f32_e32 v130, 1.0, v130
	v_add_f32_e32 v131, 1.0, v131
	v_add_f32_e32 v132, 1.0, v132
	v_add_f32_e32 v133, 1.0, v133
	v_rcp_f32_e32 v130, v130
	v_rcp_f32_e32 v131, v131
	v_rcp_f32_e32 v132, v132
	v_rcp_f32_e32 v133, v133
	v_pk_mul_f32 v[90:91], v[90:91], v[130:131]
	v_pk_mul_f32 v[92:93], v[92:93], v[132:133]
	v_cvt_pk_bf16_f32 v90, v90, v91
	v_cvt_pk_bf16_f32 v91, v92, v93
	ds_write_b64 v137, v[90:91] offset:4096
	v_mul_f32_e32 v130, 0xbfb8aa3b, v86
	v_mul_f32_e32 v131, 0xbfb8aa3b, v87
	v_mul_f32_e32 v132, 0xbfb8aa3b, v88
	v_mul_f32_e32 v133, 0xbfb8aa3b, v89
	v_exp_f32_e32 v130, v130
	v_exp_f32_e32 v131, v131
	v_exp_f32_e32 v132, v132
	v_exp_f32_e32 v133, v133
	v_add_f32_e32 v130, 1.0, v130
	v_add_f32_e32 v131, 1.0, v131
	v_add_f32_e32 v132, 1.0, v132
	v_add_f32_e32 v133, 1.0, v133
	v_rcp_f32_e32 v130, v130
	v_rcp_f32_e32 v131, v131
	v_rcp_f32_e32 v132, v132
	v_rcp_f32_e32 v133, v133
	v_pk_mul_f32 v[86:87], v[86:87], v[130:131]
	v_pk_mul_f32 v[88:89], v[88:89], v[132:133]
	v_cvt_pk_bf16_f32 v86, v86, v87
	v_cvt_pk_bf16_f32 v87, v88, v89
	ds_write_b64 v138, v[86:87] offset:4096
	v_mul_f32_e32 v130, 0xbfb8aa3b, v82
	v_mul_f32_e32 v131, 0xbfb8aa3b, v83
	v_mul_f32_e32 v132, 0xbfb8aa3b, v84
	v_mul_f32_e32 v133, 0xbfb8aa3b, v85
; __device__ __forceinline__ float siluf(float v) { return v * __builtin_amdgcn_rcpf(1.f + __builtin_amdgcn_exp2f(-1.4426950408889634f * v)); }
; __device__ __forceinline__ float sigmf(float v) { return __builtin_amdgcn_rcpf(1.f + __builtin_amdgcn_exp2f(-1.4426950408889634f * v)); }
; #define G1_STG(mi_, ni_, v_) do { const int r_ = (mi_) * 16 + idx; const f32x4 t_ = (v_); u32x2 pk_; pk_.x = pk2(t_.x, t_.y); pk_.y = pk2(t_.z, t_.w); \
;         *(u32x2*)(wl + r_ * 128 + ((((ni_) * 2 + (kq >> 1)) ^ (r_ & 7)) * 16) + (kq & 1) * 8) = pk_; } while (0)
; __device__ void gemm1_phase(const Params& p, int l, int hb, unsigned char* smem) {
;     ...
; #pragma unroll
;             for (int mi = 0; mi < 8; ++mi) {
; #pragma unroll
;                 for (int ni = 0; ni < 4; ++ni) {
;                     f32x4 v = acc[mi][ni];
;                     if (mode == 1) { v.x = siluf(v.x); v.y = siluf(v.y); v.z = siluf(v.z); v.w = siluf(v.w); }
;                     else if (mode == 2) { const f32x4 bb = *(const f32x4*)(bg + ni * 16); v.x = sigmf(v.x + bb.x); v.y = sigmf(v.y + bb.y); v.z = sigmf(v.z + bb.z); v.w = sigmf(v.w + bb.w); }
;                     G1_STG(mi, ni, v);
;                 }
;             }
;         }
;     ...
;         if (dbase) {
;             const int ch = lane & 7;
; #pragma unroll
;             for (int j = 0; j < 16; ++j) {
;                 const int rl = 8 * j + (lane >> 3), row = m0 + wm * 128 + rl;
;                 const u32x4 v = *(const u32x4*)(wl + rl * 128 + ((ch ^ (rl & 7)) * 16));
;                 size_t drow = (size_t)row;
;                 if (dsh >= 0) { const int bl = row >> 13, tt = row & (SEQ - 1); drow = (size_t)(bl * 3 + dg) * SEQ + (size_t)((tt & ((1 << dsh) - 1)) * (SEQ >> dsh) + (tt >> dsh)); }
;                 *(u32x4*)(dbase + drow * dpitch + dc0 + ch * 8) = v;
;             }
;         }
	v_exp_f32_e32 v130, v130
	v_exp_f32_e32 v131, v131
	v_exp_f32_e32 v132, v132
	v_exp_f32_e32 v133, v133
	v_add_f32_e32 v130, 1.0, v130
	v_add_f32_e32 v131, 1.0, v131
	v_add_f32_e32 v132, 1.0, v132
	v_add_f32_e32 v133, 1.0, v133
	v_rcp_f32_e32 v130, v130
	v_rcp_f32_e32 v131, v131
	v_rcp_f32_e32 v132, v132
	v_rcp_f32_e32 v133, v133
	v_pk_mul_f32 v[82:83], v[82:83], v[130:131]
	v_pk_mul_f32 v[84:85], v[84:85], v[132:133]
	v_cvt_pk_bf16_f32 v82, v82, v83
	v_cvt_pk_bf16_f32 v83, v84, v85
	ds_write_b64 v139, v[82:83] offset:4096
	v_mul_f32_e32 v130, 0xbfb8aa3b, v76
	v_mul_f32_e32 v131, 0xbfb8aa3b, v77
	v_mul_f32_e32 v132, 0xbfb8aa3b, v78
	v_mul_f32_e32 v133, 0xbfb8aa3b, v79
	v_exp_f32_e32 v130, v130
	v_exp_f32_e32 v131, v131
	v_exp_f32_e32 v132, v132
	v_exp_f32_e32 v133, v133
	v_add_f32_e32 v130, 1.0, v130
	v_add_f32_e32 v131, 1.0, v131
	v_add_f32_e32 v132, 1.0, v132
	v_add_f32_e32 v133, 1.0, v133
	v_rcp_f32_e32 v130, v130
	v_rcp_f32_e32 v131, v131
	v_rcp_f32_e32 v132, v132
	v_rcp_f32_e32 v133, v133
	v_pk_mul_f32 v[76:77], v[76:77], v[130:131]
	v_pk_mul_f32 v[78:79], v[78:79], v[132:133]
	v_cvt_pk_bf16_f32 v76, v76, v77
	v_cvt_pk_bf16_f32 v77, v78, v79
	ds_write_b64 v136, v[76:77] offset:6144
	v_mul_f32_e32 v130, 0xbfb8aa3b, v72
	v_mul_f32_e32 v131, 0xbfb8aa3b, v73
	v_mul_f32_e32 v132, 0xbfb8aa3b, v74
	v_mul_f32_e32 v133, 0xbfb8aa3b, v75
	v_exp_f32_e32 v130, v130
	v_exp_f32_e32 v131, v131
	v_exp_f32_e32 v132, v132
	v_exp_f32_e32 v133, v133
	v_add_f32_e32 v130, 1.0, v130
	v_add_f32_e32 v131, 1.0, v131
	v_add_f32_e32 v132, 1.0, v132
	v_add_f32_e32 v133, 1.0, v133
	v_rcp_f32_e32 v130, v130
	v_rcp_f32_e32 v131, v131
	v_rcp_f32_e32 v132, v132
	v_rcp_f32_e32 v133, v133
	v_pk_mul_f32 v[72:73], v[72:73], v[130:131]
	v_pk_mul_f32 v[74:75], v[74:75], v[132:133]
	v_cvt_pk_bf16_f32 v72, v72, v73
	v_cvt_pk_bf16_f32 v73, v74, v75
	ds_write_b64 v137, v[72:73] offset:6144
	v_mul_f32_e32 v130, 0xbfb8aa3b, v68
	v_mul_f32_e32 v131, 0xbfb8aa3b, v69
	v_mul_f32_e32 v132, 0xbfb8aa3b, v70
	v_mul_f32_e32 v133, 0xbfb8aa3b, v71
	v_exp_f32_e32 v130, v130
	v_exp_f32_e32 v131, v131
	v_exp_f32_e32 v132, v132
	v_exp_f32_e32 v133, v133
	v_add_f32_e32 v130, 1.0, v130
	v_add_f32_e32 v131, 1.0, v131
	v_add_f32_e32 v132, 1.0, v132
	v_add_f32_e32 v133, 1.0, v133
	v_rcp_f32_e32 v130, v130
	v_rcp_f32_e32 v131, v131
	v_rcp_f32_e32 v132, v132
	v_rcp_f32_e32 v133, v133
	v_pk_mul_f32 v[68:69], v[68:69], v[130:131]
	v_pk_mul_f32 v[70:71], v[70:71], v[132:133]
	v_cvt_pk_bf16_f32 v68, v68, v69
	v_cvt_pk_bf16_f32 v69, v70, v71
	ds_write_b64 v138, v[68:69] offset:6144
	v_mul_f32_e32 v130, 0xbfb8aa3b, v64
	v_mul_f32_e32 v131, 0xbfb8aa3b, v65
	v_mul_f32_e32 v132, 0xbfb8aa3b, v66
	v_mul_f32_e32 v133, 0xbfb8aa3b, v67
	v_exp_f32_e32 v130, v130
	v_exp_f32_e32 v131, v131
	v_exp_f32_e32 v132, v132
	v_exp_f32_e32 v133, v133
	v_add_f32_e32 v130, 1.0, v130
	v_add_f32_e32 v131, 1.0, v131
	v_add_f32_e32 v132, 1.0, v132
	v_add_f32_e32 v133, 1.0, v133
	v_rcp_f32_e32 v130, v130
	v_rcp_f32_e32 v131, v131
	v_rcp_f32_e32 v132, v132
	v_rcp_f32_e32 v133, v133
	v_pk_mul_f32 v[64:65], v[64:65], v[130:131]
	v_pk_mul_f32 v[66:67], v[66:67], v[132:133]
	v_cvt_pk_bf16_f32 v64, v64, v65
	v_cvt_pk_bf16_f32 v65, v66, v67
	ds_write_b64 v139, v[64:65] offset:6144
	ds_read_b128 v[98:101], v144
	ds_read_b128 v[102:105], v144 offset:1024
	ds_read_b128 v[106:109], v144 offset:2048
	ds_read_b128 v[110:113], v144 offset:3072
	ds_read_b128 v[114:117], v144 offset:4096
	ds_read_b128 v[118:121], v144 offset:5120
	ds_read_b128 v[122:125], v144 offset:6144
	ds_read_b128 v[126:129], v144 offset:7168
	s_waitcnt lgkmcnt(7)
	global_store_dwordx4 v145, v[98:101], s[90:91]
	v_add_u32_e32 v145, s100, v145
	s_waitcnt lgkmcnt(6)
	global_store_dwordx4 v145, v[102:105], s[90:91]
	v_add_u32_e32 v145, s100, v145
	s_waitcnt lgkmcnt(5)
	global_store_dwordx4 v145, v[106:109], s[90:91]
	v_add_u32_e32 v145, s100, v145
	s_waitcnt lgkmcnt(4)
	global_store_dwordx4 v145, v[110:113], s[90:91]
	v_add_u32_e32 v145, s100, v145
	s_waitcnt lgkmcnt(3)
	global_store_dwordx4 v145, v[114:117], s[90:91]
	v_add_u32_e32 v145, s100, v145
	s_waitcnt lgkmcnt(2)
	global_store_dwordx4 v145, v[118:121], s[90:91]
	v_add_u32_e32 v145, s100, v145
	s_waitcnt lgkmcnt(1)
	global_store_dwordx4 v145, v[122:125], s[90:91]
	v_add_u32_e32 v145, s100, v145
	s_waitcnt lgkmcnt(0)
; __device__ __forceinline__ float siluf(float v) { return v * __builtin_amdgcn_rcpf(1.f + __builtin_amdgcn_exp2f(-1.4426950408889634f * v)); }
; __device__ __forceinline__ float sigmf(float v) { return __builtin_amdgcn_rcpf(1.f + __builtin_amdgcn_exp2f(-1.4426950408889634f * v)); }
; #define G1_STG(mi_, ni_, v_) do { const int r_ = (mi_) * 16 + idx; const f32x4 t_ = (v_); u32x2 pk_; pk_.x = pk2(t_.x, t_.y); pk_.y = pk2(t_.z, t_.w); \
;         *(u32x2*)(wl + r_ * 128 + ((((ni_) * 2 + (kq >> 1)) ^ (r_ & 7)) * 16) + (kq & 1) * 8) = pk_; } while (0)
; __device__ void gemm1_phase(const Params& p, int l, int hb, unsigned char* smem) {
;     ...
; #pragma unroll
;             for (int mi = 0; mi < 8; ++mi) {
; #pragma unroll
;                 for (int ni = 0; ni < 4; ++ni) {
;                     f32x4 v = acc[mi][ni];
;                     if (mode == 1) { v.x = siluf(v.x); v.y = siluf(v.y); v.z = siluf(v.z); v.w = siluf(v.w); }
;                     else if (mode == 2) { const f32x4 bb = *(const f32x4*)(bg + ni * 16); v.x = sigmf(v.x + bb.x); v.y = sigmf(v.y + bb.y); v.z = sigmf(v.z + bb.z); v.w = sigmf(v.w + bb.w); }
;                     G1_STG(mi, ni, v);
;                 }
;             }
;         }
;     ...
;         if (dbase) {
;             const int ch = lane & 7;
; #pragma unroll
;             for (int j = 0; j < 16; ++j) {
;                 const int rl = 8 * j + (lane >> 3), row = m0 + wm * 128 + rl;
;                 const u32x4 v = *(const u32x4*)(wl + rl * 128 + ((ch ^ (rl & 7)) * 16));
;                 size_t drow = (size_t)row;
;                 if (dsh >= 0) { const int bl = row >> 13, tt = row & (SEQ - 1); drow = (size_t)(bl * 3 + dg) * SEQ + (size_t)((tt & ((1 << dsh) - 1)) * (SEQ >> dsh) + (tt >> dsh)); }
;                 *(u32x4*)(dbase + drow * dpitch + dc0 + ch * 8) = v;
;             }
;         }
	global_store_dwordx4 v145, v[126:129], s[90:91]
	v_add_u32_e32 v145, s100, v145
	v_mul_f32_e32 v130, 0xbfb8aa3b, v60
	v_mul_f32_e32 v131, 0xbfb8aa3b, v61
	v_mul_f32_e32 v132, 0xbfb8aa3b, v62
	v_mul_f32_e32 v133, 0xbfb8aa3b, v63
	v_exp_f32_e32 v130, v130
	v_exp_f32_e32 v131, v131
	v_exp_f32_e32 v132, v132
	v_exp_f32_e32 v133, v133
	v_add_f32_e32 v130, 1.0, v130
	v_add_f32_e32 v131, 1.0, v131
	v_add_f32_e32 v132, 1.0, v132
	v_add_f32_e32 v133, 1.0, v133
	v_rcp_f32_e32 v130, v130
	v_rcp_f32_e32 v131, v131
	v_rcp_f32_e32 v132, v132
	v_rcp_f32_e32 v133, v133
	v_pk_mul_f32 v[60:61], v[60:61], v[130:131]
	v_pk_mul_f32 v[62:63], v[62:63], v[132:133]
	v_cvt_pk_bf16_f32 v60, v60, v61
	v_cvt_pk_bf16_f32 v61, v62, v63
	ds_write_b64 v136, v[60:61]
	v_mul_f32_e32 v130, 0xbfb8aa3b, v56
	v_mul_f32_e32 v131, 0xbfb8aa3b, v57
	v_mul_f32_e32 v132, 0xbfb8aa3b, v58
	v_mul_f32_e32 v133, 0xbfb8aa3b, v59
	v_exp_f32_e32 v130, v130
	v_exp_f32_e32 v131, v131
	v_exp_f32_e32 v132, v132
	v_exp_f32_e32 v133, v133
	v_add_f32_e32 v130, 1.0, v130
	v_add_f32_e32 v131, 1.0, v131
	v_add_f32_e32 v132, 1.0, v132
	v_add_f32_e32 v133, 1.0, v133
	v_rcp_f32_e32 v130, v130
	v_rcp_f32_e32 v131, v131
	v_rcp_f32_e32 v132, v132
	v_rcp_f32_e32 v133, v133
	v_pk_mul_f32 v[56:57], v[56:57], v[130:131]
	v_pk_mul_f32 v[58:59], v[58:59], v[132:133]
	v_cvt_pk_bf16_f32 v56, v56, v57
	v_cvt_pk_bf16_f32 v57, v58, v59
	ds_write_b64 v137, v[56:57]
	v_mul_f32_e32 v130, 0xbfb8aa3b, v52
	v_mul_f32_e32 v131, 0xbfb8aa3b, v53
	v_mul_f32_e32 v132, 0xbfb8aa3b, v54
	v_mul_f32_e32 v133, 0xbfb8aa3b, v55
	v_exp_f32_e32 v130, v130
	v_exp_f32_e32 v131, v131
	v_exp_f32_e32 v132, v132
	v_exp_f32_e32 v133, v133
	v_add_f32_e32 v130, 1.0, v130
	v_add_f32_e32 v131, 1.0, v131
	v_add_f32_e32 v132, 1.0, v132
	v_add_f32_e32 v133, 1.0, v133
	v_rcp_f32_e32 v130, v130
	v_rcp_f32_e32 v131, v131
	v_rcp_f32_e32 v132, v132
	v_rcp_f32_e32 v133, v133
	v_pk_mul_f32 v[52:53], v[52:53], v[130:131]
	v_pk_mul_f32 v[54:55], v[54:55], v[132:133]
	v_cvt_pk_bf16_f32 v52, v52, v53
	v_cvt_pk_bf16_f32 v53, v54, v55
	ds_write_b64 v138, v[52:53]
	v_mul_f32_e32 v130, 0xbfb8aa3b, v48
	v_mul_f32_e32 v131, 0xbfb8aa3b, v49
	v_mul_f32_e32 v132, 0xbfb8aa3b, v50
	v_mul_f32_e32 v133, 0xbfb8aa3b, v51
	v_exp_f32_e32 v130, v130
	v_exp_f32_e32 v131, v131
	v_exp_f32_e32 v132, v132
	v_exp_f32_e32 v133, v133
	v_add_f32_e32 v130, 1.0, v130
	v_add_f32_e32 v131, 1.0, v131
	v_add_f32_e32 v132, 1.0, v132
	v_add_f32_e32 v133, 1.0, v133
	v_rcp_f32_e32 v130, v130
	v_rcp_f32_e32 v131, v131
	v_rcp_f32_e32 v132, v132
	v_rcp_f32_e32 v133, v133
	v_pk_mul_f32 v[48:49], v[48:49], v[130:131]
	v_pk_mul_f32 v[50:51], v[50:51], v[132:133]
	v_cvt_pk_bf16_f32 v48, v48, v49
	v_cvt_pk_bf16_f32 v49, v50, v51
	ds_write_b64 v139, v[48:49]
	v_mul_f32_e32 v130, 0xbfb8aa3b, v44
	v_mul_f32_e32 v131, 0xbfb8aa3b, v45
	v_mul_f32_e32 v132, 0xbfb8aa3b, v46
	v_mul_f32_e32 v133, 0xbfb8aa3b, v47
	v_exp_f32_e32 v130, v130
	v_exp_f32_e32 v131, v131
	v_exp_f32_e32 v132, v132
	v_exp_f32_e32 v133, v133
	v_add_f32_e32 v130, 1.0, v130
	v_add_f32_e32 v131, 1.0, v131
	v_add_f32_e32 v132, 1.0, v132
	v_add_f32_e32 v133, 1.0, v133
	v_rcp_f32_e32 v130, v130
	v_rcp_f32_e32 v131, v131
	v_rcp_f32_e32 v132, v132
	v_rcp_f32_e32 v133, v133
	v_pk_mul_f32 v[44:45], v[44:45], v[130:131]
	v_pk_mul_f32 v[46:47], v[46:47], v[132:133]
	v_cvt_pk_bf16_f32 v44, v44, v45
	v_cvt_pk_bf16_f32 v45, v46, v47
	ds_write_b64 v136, v[44:45] offset:2048
	v_mul_f32_e32 v130, 0xbfb8aa3b, v40
	v_mul_f32_e32 v131, 0xbfb8aa3b, v41
	v_mul_f32_e32 v132, 0xbfb8aa3b, v42
	v_mul_f32_e32 v133, 0xbfb8aa3b, v43
	v_exp_f32_e32 v130, v130
	v_exp_f32_e32 v131, v131
	v_exp_f32_e32 v132, v132
	v_exp_f32_e32 v133, v133
	v_add_f32_e32 v130, 1.0, v130
	v_add_f32_e32 v131, 1.0, v131
	v_add_f32_e32 v132, 1.0, v132
	v_add_f32_e32 v133, 1.0, v133
	v_rcp_f32_e32 v130, v130
	v_rcp_f32_e32 v131, v131
	v_rcp_f32_e32 v132, v132
	v_rcp_f32_e32 v133, v133
	v_pk_mul_f32 v[40:41], v[40:41], v[130:131]
	v_pk_mul_f32 v[42:43], v[42:43], v[132:133]
	v_cvt_pk_bf16_f32 v40, v40, v41
	v_cvt_pk_bf16_f32 v41, v42, v43
	ds_write_b64 v137, v[40:41] offset:2048
	v_mul_f32_e32 v130, 0xbfb8aa3b, v36
	v_mul_f32_e32 v131, 0xbfb8aa3b, v37
	v_mul_f32_e32 v132, 0xbfb8aa3b, v38
	v_mul_f32_e32 v133, 0xbfb8aa3b, v39
	v_exp_f32_e32 v130, v130
	v_exp_f32_e32 v131, v131
	v_exp_f32_e32 v132, v132
	v_exp_f32_e32 v133, v133
	v_add_f32_e32 v130, 1.0, v130
	v_add_f32_e32 v131, 1.0, v131
	v_add_f32_e32 v132, 1.0, v132
	v_add_f32_e32 v133, 1.0, v133
	v_rcp_f32_e32 v130, v130
	v_rcp_f32_e32 v131, v131
	v_rcp_f32_e32 v132, v132
	v_rcp_f32_e32 v133, v133
	v_pk_mul_f32 v[36:37], v[36:37], v[130:131]
	v_pk_mul_f32 v[38:39], v[38:39], v[132:133]
	v_cvt_pk_bf16_f32 v36, v36, v37
	v_cvt_pk_bf16_f32 v37, v38, v39
	ds_write_b64 v138, v[36:37] offset:2048
	v_mul_f32_e32 v130, 0xbfb8aa3b, v32
	v_mul_f32_e32 v131, 0xbfb8aa3b, v33
	v_mul_f32_e32 v132, 0xbfb8aa3b, v34
	v_mul_f32_e32 v133, 0xbfb8aa3b, v35
	v_exp_f32_e32 v130, v130
	v_exp_f32_e32 v131, v131
	v_exp_f32_e32 v132, v132
	v_exp_f32_e32 v133, v133
	v_add_f32_e32 v130, 1.0, v130
	v_add_f32_e32 v131, 1.0, v131
	v_add_f32_e32 v132, 1.0, v132
	v_add_f32_e32 v133, 1.0, v133
	v_rcp_f32_e32 v130, v130
	v_rcp_f32_e32 v131, v131
	v_rcp_f32_e32 v132, v132
	v_rcp_f32_e32 v133, v133
	v_pk_mul_f32 v[32:33], v[32:33], v[130:131]
	v_pk_mul_f32 v[34:35], v[34:35], v[132:133]
	v_cvt_pk_bf16_f32 v32, v32, v33
	v_cvt_pk_bf16_f32 v33, v34, v35
	ds_write_b64 v139, v[32:33] offset:2048
	v_mul_f32_e32 v130, 0xbfb8aa3b, v28
	v_mul_f32_e32 v131, 0xbfb8aa3b, v29
	v_mul_f32_e32 v132, 0xbfb8aa3b, v30
	v_mul_f32_e32 v133, 0xbfb8aa3b, v31
	v_exp_f32_e32 v130, v130
	v_exp_f32_e32 v131, v131
; __device__ __forceinline__ float siluf(float v) { return v * __builtin_amdgcn_rcpf(1.f + __builtin_amdgcn_exp2f(-1.4426950408889634f * v)); }
; __device__ __forceinline__ float sigmf(float v) { return __builtin_amdgcn_rcpf(1.f + __builtin_amdgcn_exp2f(-1.4426950408889634f * v)); }
; #define G1_STG(mi_, ni_, v_) do { const int r_ = (mi_) * 16 + idx; const f32x4 t_ = (v_); u32x2 pk_; pk_.x = pk2(t_.x, t_.y); pk_.y = pk2(t_.z, t_.w); \
;         *(u32x2*)(wl + r_ * 128 + ((((ni_) * 2 + (kq >> 1)) ^ (r_ & 7)) * 16) + (kq & 1) * 8) = pk_; } while (0)
; __device__ void gemm1_phase(const Params& p, int l, int hb, unsigned char* smem) {
;     ...
; #pragma unroll
;             for (int mi = 0; mi < 8; ++mi) {
; #pragma unroll
;                 for (int ni = 0; ni < 4; ++ni) {
;                     f32x4 v = acc[mi][ni];
;                     if (mode == 1) { v.x = siluf(v.x); v.y = siluf(v.y); v.z = siluf(v.z); v.w = siluf(v.w); }
;                     else if (mode == 2) { const f32x4 bb = *(const f32x4*)(bg + ni * 16); v.x = sigmf(v.x + bb.x); v.y = sigmf(v.y + bb.y); v.z = sigmf(v.z + bb.z); v.w = sigmf(v.w + bb.w); }
;                     G1_STG(mi, ni, v);
;                 }
;             }
;         }
;     ...
;         if (dbase) {
;             const int ch = lane & 7;
; #pragma unroll
;             for (int j = 0; j < 16; ++j) {
;                 const int rl = 8 * j + (lane >> 3), row = m0 + wm * 128 + rl;
;                 const u32x4 v = *(const u32x4*)(wl + rl * 128 + ((ch ^ (rl & 7)) * 16));
;                 size_t drow = (size_t)row;
;                 if (dsh >= 0) { const int bl = row >> 13, tt = row & (SEQ - 1); drow = (size_t)(bl * 3 + dg) * SEQ + (size_t)((tt & ((1 << dsh) - 1)) * (SEQ >> dsh) + (tt >> dsh)); }
;                 *(u32x4*)(dbase + drow * dpitch + dc0 + ch * 8) = v;
;             }
;         }
	v_exp_f32_e32 v132, v132
	v_exp_f32_e32 v133, v133
	v_add_f32_e32 v130, 1.0, v130
	v_add_f32_e32 v131, 1.0, v131
	v_add_f32_e32 v132, 1.0, v132
	v_add_f32_e32 v133, 1.0, v133
	v_rcp_f32_e32 v130, v130
	v_rcp_f32_e32 v131, v131
	v_rcp_f32_e32 v132, v132
	v_rcp_f32_e32 v133, v133
	v_pk_mul_f32 v[28:29], v[28:29], v[130:131]
	v_pk_mul_f32 v[30:31], v[30:31], v[132:133]
	v_cvt_pk_bf16_f32 v28, v28, v29
	v_cvt_pk_bf16_f32 v29, v30, v31
	ds_write_b64 v136, v[28:29] offset:4096
	v_mul_f32_e32 v130, 0xbfb8aa3b, v24
	v_mul_f32_e32 v131, 0xbfb8aa3b, v25
	v_mul_f32_e32 v132, 0xbfb8aa3b, v26
	v_mul_f32_e32 v133, 0xbfb8aa3b, v27
	v_exp_f32_e32 v130, v130
	v_exp_f32_e32 v131, v131
	v_exp_f32_e32 v132, v132
	v_exp_f32_e32 v133, v133
	v_add_f32_e32 v130, 1.0, v130
	v_add_f32_e32 v131, 1.0, v131
	v_add_f32_e32 v132, 1.0, v132
	v_add_f32_e32 v133, 1.0, v133
	v_rcp_f32_e32 v130, v130
	v_rcp_f32_e32 v131, v131
	v_rcp_f32_e32 v132, v132
	v_rcp_f32_e32 v133, v133
	v_pk_mul_f32 v[24:25], v[24:25], v[130:131]
	v_pk_mul_f32 v[26:27], v[26:27], v[132:133]
	v_cvt_pk_bf16_f32 v24, v24, v25
	v_cvt_pk_bf16_f32 v25, v26, v27
	ds_write_b64 v137, v[24:25] offset:4096
	v_mul_f32_e32 v130, 0xbfb8aa3b, v20
	v_mul_f32_e32 v131, 0xbfb8aa3b, v21
	v_mul_f32_e32 v132, 0xbfb8aa3b, v22
	v_mul_f32_e32 v133, 0xbfb8aa3b, v23
	v_exp_f32_e32 v130, v130
	v_exp_f32_e32 v131, v131
	v_exp_f32_e32 v132, v132
	v_exp_f32_e32 v133, v133
	v_add_f32_e32 v130, 1.0, v130
	v_add_f32_e32 v131, 1.0, v131
	v_add_f32_e32 v132, 1.0, v132
	v_add_f32_e32 v133, 1.0, v133
	v_rcp_f32_e32 v130, v130
	v_rcp_f32_e32 v131, v131
	v_rcp_f32_e32 v132, v132
	v_rcp_f32_e32 v133, v133
	v_pk_mul_f32 v[20:21], v[20:21], v[130:131]
	v_pk_mul_f32 v[22:23], v[22:23], v[132:133]
	v_cvt_pk_bf16_f32 v20, v20, v21
	v_cvt_pk_bf16_f32 v21, v22, v23
	ds_write_b64 v138, v[20:21] offset:4096
	v_mul_f32_e32 v130, 0xbfb8aa3b, v16
	v_mul_f32_e32 v131, 0xbfb8aa3b, v17
	v_mul_f32_e32 v132, 0xbfb8aa3b, v18
	v_mul_f32_e32 v133, 0xbfb8aa3b, v19
	v_exp_f32_e32 v130, v130
	v_exp_f32_e32 v131, v131
	v_exp_f32_e32 v132, v132
	v_exp_f32_e32 v133, v133
	v_add_f32_e32 v130, 1.0, v130
	v_add_f32_e32 v131, 1.0, v131
	v_add_f32_e32 v132, 1.0, v132
	v_add_f32_e32 v133, 1.0, v133
	v_rcp_f32_e32 v130, v130
	v_rcp_f32_e32 v131, v131
	v_rcp_f32_e32 v132, v132
	v_rcp_f32_e32 v133, v133
	v_pk_mul_f32 v[16:17], v[16:17], v[130:131]
	v_pk_mul_f32 v[18:19], v[18:19], v[132:133]
	v_cvt_pk_bf16_f32 v16, v16, v17
	v_cvt_pk_bf16_f32 v17, v18, v19
	ds_write_b64 v139, v[16:17] offset:4096
	v_mul_f32_e32 v130, 0xbfb8aa3b, v12
	v_mul_f32_e32 v131, 0xbfb8aa3b, v13
	v_mul_f32_e32 v132, 0xbfb8aa3b, v14
	v_mul_f32_e32 v133, 0xbfb8aa3b, v15
	v_exp_f32_e32 v130, v130
	v_exp_f32_e32 v131, v131
	v_exp_f32_e32 v132, v132
	v_exp_f32_e32 v133, v133
	v_add_f32_e32 v130, 1.0, v130
	v_add_f32_e32 v131, 1.0, v131
	v_add_f32_e32 v132, 1.0, v132
	v_add_f32_e32 v133, 1.0, v133
	v_rcp_f32_e32 v130, v130
	v_rcp_f32_e32 v131, v131
	v_rcp_f32_e32 v132, v132
	v_rcp_f32_e32 v133, v133
	v_pk_mul_f32 v[12:13], v[12:13], v[130:131]
	v_pk_mul_f32 v[14:15], v[14:15], v[132:133]
	v_cvt_pk_bf16_f32 v12, v12, v13
	v_cvt_pk_bf16_f32 v13, v14, v15
	ds_write_b64 v136, v[12:13] offset:6144
	v_mul_f32_e32 v130, 0xbfb8aa3b, v8
	v_mul_f32_e32 v131, 0xbfb8aa3b, v9
	v_mul_f32_e32 v132, 0xbfb8aa3b, v10
	v_mul_f32_e32 v133, 0xbfb8aa3b, v11
	v_exp_f32_e32 v130, v130
	v_exp_f32_e32 v131, v131
	v_exp_f32_e32 v132, v132
	v_exp_f32_e32 v133, v133
	v_add_f32_e32 v130, 1.0, v130
	v_add_f32_e32 v131, 1.0, v131
	v_add_f32_e32 v132, 1.0, v132
	v_add_f32_e32 v133, 1.0, v133
	v_rcp_f32_e32 v130, v130
	v_rcp_f32_e32 v131, v131
	v_rcp_f32_e32 v132, v132
	v_rcp_f32_e32 v133, v133
	v_pk_mul_f32 v[8:9], v[8:9], v[130:131]
	v_pk_mul_f32 v[10:11], v[10:11], v[132:133]
	v_cvt_pk_bf16_f32 v8, v8, v9
	v_cvt_pk_bf16_f32 v9, v10, v11
	ds_write_b64 v137, v[8:9] offset:6144
	v_mul_f32_e32 v130, 0xbfb8aa3b, v4
	v_mul_f32_e32 v131, 0xbfb8aa3b, v5
	v_mul_f32_e32 v132, 0xbfb8aa3b, v6
	v_mul_f32_e32 v133, 0xbfb8aa3b, v7
	v_exp_f32_e32 v130, v130
	v_exp_f32_e32 v131, v131
	v_exp_f32_e32 v132, v132
	v_exp_f32_e32 v133, v133
	v_add_f32_e32 v130, 1.0, v130
	v_add_f32_e32 v131, 1.0, v131
	v_add_f32_e32 v132, 1.0, v132
	v_add_f32_e32 v133, 1.0, v133
	v_rcp_f32_e32 v130, v130
	v_rcp_f32_e32 v131, v131
	v_rcp_f32_e32 v132, v132
	v_rcp_f32_e32 v133, v133
	v_pk_mul_f32 v[4:5], v[4:5], v[130:131]
	v_pk_mul_f32 v[6:7], v[6:7], v[132:133]
	v_cvt_pk_bf16_f32 v4, v4, v5
	v_cvt_pk_bf16_f32 v5, v6, v7
	ds_write_b64 v138, v[4:5] offset:6144
	v_mul_f32_e32 v130, 0xbfb8aa3b, v0
	v_mul_f32_e32 v131, 0xbfb8aa3b, v1
	v_mul_f32_e32 v132, 0xbfb8aa3b, v2
	v_mul_f32_e32 v133, 0xbfb8aa3b, v3
	v_exp_f32_e32 v130, v130
	v_exp_f32_e32 v131, v131
	v_exp_f32_e32 v132, v132
	v_exp_f32_e32 v133, v133
	v_add_f32_e32 v130, 1.0, v130
	v_add_f32_e32 v131, 1.0, v131
	v_add_f32_e32 v132, 1.0, v132
	v_add_f32_e32 v133, 1.0, v133
	v_rcp_f32_e32 v130, v130
	v_rcp_f32_e32 v131, v131
	v_rcp_f32_e32 v132, v132
	v_rcp_f32_e32 v133, v133
	v_pk_mul_f32 v[0:1], v[0:1], v[130:131]
	v_pk_mul_f32 v[2:3], v[2:3], v[132:133]
	v_cvt_pk_bf16_f32 v0, v0, v1
	v_cvt_pk_bf16_f32 v1, v2, v3
	ds_write_b64 v139, v[0:1] offset:6144
	ds_read_b128 v[0:3], v144
	ds_read_b128 v[4:7], v144 offset:1024
	ds_read_b128 v[8:11], v144 offset:2048
	ds_read_b128 v[12:15], v144 offset:3072
	ds_read_b128 v[16:19], v144 offset:4096
	ds_read_b128 v[20:23], v144 offset:5120
	ds_read_b128 v[24:27], v144 offset:6144
	ds_read_b128 v[28:31], v144 offset:7168
	s_waitcnt lgkmcnt(7)
	global_store_dwordx4 v145, v[0:3], s[90:91]
	v_add_u32_e32 v145, s100, v145
	s_waitcnt lgkmcnt(6)
	global_store_dwordx4 v145, v[4:7], s[90:91]
	v_add_u32_e32 v145, s100, v145
	s_waitcnt lgkmcnt(5)
	global_store_dwordx4 v145, v[8:11], s[90:91]
	v_add_u32_e32 v145, s100, v145
	s_waitcnt lgkmcnt(4)
	global_store_dwordx4 v145, v[12:15], s[90:91]
	v_add_u32_e32 v145, s100, v145
	s_waitcnt lgkmcnt(3)
	global_store_dwordx4 v145, v[16:19], s[90:91]
	v_add_u32_e32 v145, s100, v145
	s_waitcnt lgkmcnt(2)
	global_store_dwordx4 v145, v[20:23], s[90:91]
	v_add_u32_e32 v145, s100, v145
	s_waitcnt lgkmcnt(1)
	global_store_dwordx4 v145, v[24:27], s[90:91]
	v_add_u32_e32 v145, s100, v145
	s_waitcnt lgkmcnt(0)
	global_store_dwordx4 v145, v[28:31], s[90:91]
	v_add_u32_e32 v145, s100, v145
	s_branch .LBB0_253
; __device__ __forceinline__ float siluf(float v) { return v * __builtin_amdgcn_rcpf(1.f + __builtin_amdgcn_exp2f(-1.4426950408889634f * v)); }
; __device__ __forceinline__ float sigmf(float v) { return __builtin_amdgcn_rcpf(1.f + __builtin_amdgcn_exp2f(-1.4426950408889634f * v)); }
; #define G1_STG(mi_, ni_, v_) do { const int r_ = (mi_) * 16 + idx; const f32x4 t_ = (v_); u32x2 pk_; pk_.x = pk2(t_.x, t_.y); pk_.y = pk2(t_.z, t_.w); \
;         *(u32x2*)(wl + r_ * 128 + ((((ni_) * 2 + (kq >> 1)) ^ (r_ & 7)) * 16) + (kq & 1) * 8) = pk_; } while (0)
; __device__ void gemm1_phase(const Params& p, int l, int hb, unsigned char* smem) {
;     ...
;             const float* bg = p.b_gate + l * 3072 + dc0 + lc;
; #pragma unroll
;             for (int mi = 0; mi < 8; ++mi) {
; #pragma unroll
;                 for (int ni = 0; ni < 4; ++ni) {
;                     f32x4 v = acc[mi][ni];
;                     if (mode == 1) { v.x = siluf(v.x); v.y = siluf(v.y); v.z = siluf(v.z); v.w = siluf(v.w); }
;                     else if (mode == 2) { const f32x4 bb = *(const f32x4*)(bg + ni * 16); v.x = sigmf(v.x + bb.x); v.y = sigmf(v.y + bb.y); v.z = sigmf(v.z + bb.z); v.w = sigmf(v.w + bb.w); }
;                     G1_STG(mi, ni, v);
;                 }
.Lg1e_sig:
	s_cmp_lg_u32 s98, 0
	s_cbranch_scc1 .Lg1e_w8
	s_waitcnt vmcnt(0)
	s_branch .Lg1e_wd
.Lg1e_w8:
	s_waitcnt vmcnt(8)
.Lg1e_wd:
	v_add_f32_e32 v130, v126, v160
	v_add_f32_e32 v131, v127, v161
	v_add_f32_e32 v132, v128, v162
	v_add_f32_e32 v133, v129, v163
	v_mul_f32_e32 v130, 0xbfb8aa3b, v130
	v_mul_f32_e32 v131, 0xbfb8aa3b, v131
	v_mul_f32_e32 v132, 0xbfb8aa3b, v132
	v_mul_f32_e32 v133, 0xbfb8aa3b, v133
	v_exp_f32_e32 v130, v130
	v_exp_f32_e32 v131, v131
	v_exp_f32_e32 v132, v132
	v_exp_f32_e32 v133, v133
	v_add_f32_e32 v130, 1.0, v130
	v_add_f32_e32 v131, 1.0, v131
	v_add_f32_e32 v132, 1.0, v132
	v_add_f32_e32 v133, 1.0, v133
	v_rcp_f32_e32 v130, v130
	v_rcp_f32_e32 v131, v131
	v_rcp_f32_e32 v132, v132
	v_rcp_f32_e32 v133, v133
	s_nop 0
	v_cvt_pk_bf16_f32 v126, v130, v131
	v_cvt_pk_bf16_f32 v127, v132, v133
	ds_write_b64 v136, v[126:127]
	v_add_f32_e32 v130, v122, v164
	v_add_f32_e32 v131, v123, v165
	v_add_f32_e32 v132, v124, v166
	v_add_f32_e32 v133, v125, v167
	v_mul_f32_e32 v130, 0xbfb8aa3b, v130
	v_mul_f32_e32 v131, 0xbfb8aa3b, v131
	v_mul_f32_e32 v132, 0xbfb8aa3b, v132
	v_mul_f32_e32 v133, 0xbfb8aa3b, v133
	v_exp_f32_e32 v130, v130
	v_exp_f32_e32 v131, v131
	v_exp_f32_e32 v132, v132
	v_exp_f32_e32 v133, v133
	v_add_f32_e32 v130, 1.0, v130
	v_add_f32_e32 v131, 1.0, v131
	v_add_f32_e32 v132, 1.0, v132
	v_add_f32_e32 v133, 1.0, v133
	v_rcp_f32_e32 v130, v130
	v_rcp_f32_e32 v131, v131
	v_rcp_f32_e32 v132, v132
	v_rcp_f32_e32 v133, v133
	s_nop 0
	v_cvt_pk_bf16_f32 v122, v130, v131
	v_cvt_pk_bf16_f32 v123, v132, v133
	ds_write_b64 v137, v[122:123]
	v_add_f32_e32 v130, v118, v168
	v_add_f32_e32 v131, v119, v169
	v_add_f32_e32 v132, v120, v170
	v_add_f32_e32 v133, v121, v171
	v_mul_f32_e32 v130, 0xbfb8aa3b, v130
	v_mul_f32_e32 v131, 0xbfb8aa3b, v131
	v_mul_f32_e32 v132, 0xbfb8aa3b, v132
	v_mul_f32_e32 v133, 0xbfb8aa3b, v133
	v_exp_f32_e32 v130, v130
	v_exp_f32_e32 v131, v131
	v_exp_f32_e32 v132, v132
	v_exp_f32_e32 v133, v133
	v_add_f32_e32 v130, 1.0, v130
	v_add_f32_e32 v131, 1.0, v131
	v_add_f32_e32 v132, 1.0, v132
	v_add_f32_e32 v133, 1.0, v133
	v_rcp_f32_e32 v130, v130
	v_rcp_f32_e32 v131, v131
	v_rcp_f32_e32 v132, v132
	v_rcp_f32_e32 v133, v133
	s_nop 0
	v_cvt_pk_bf16_f32 v118, v130, v131
	v_cvt_pk_bf16_f32 v119, v132, v133
	ds_write_b64 v138, v[118:119]
	v_add_f32_e32 v130, v114, v172
	v_add_f32_e32 v131, v115, v173
	v_add_f32_e32 v132, v116, v174
	v_add_f32_e32 v133, v117, v175
	v_mul_f32_e32 v130, 0xbfb8aa3b, v130
	v_mul_f32_e32 v131, 0xbfb8aa3b, v131
	v_mul_f32_e32 v132, 0xbfb8aa3b, v132
	v_mul_f32_e32 v133, 0xbfb8aa3b, v133
	v_exp_f32_e32 v130, v130
	v_exp_f32_e32 v131, v131
	v_exp_f32_e32 v132, v132
	v_exp_f32_e32 v133, v133
	v_add_f32_e32 v130, 1.0, v130
	v_add_f32_e32 v131, 1.0, v131
	v_add_f32_e32 v132, 1.0, v132
	v_add_f32_e32 v133, 1.0, v133
	v_rcp_f32_e32 v130, v130
	v_rcp_f32_e32 v131, v131
	v_rcp_f32_e32 v132, v132
	v_rcp_f32_e32 v133, v133
	s_nop 0
	v_cvt_pk_bf16_f32 v114, v130, v131
	v_cvt_pk_bf16_f32 v115, v132, v133
	ds_write_b64 v139, v[114:115]
	v_add_f32_e32 v130, v110, v160
	v_add_f32_e32 v131, v111, v161
	v_add_f32_e32 v132, v112, v162
	v_add_f32_e32 v133, v113, v163
	v_mul_f32_e32 v130, 0xbfb8aa3b, v130
	v_mul_f32_e32 v131, 0xbfb8aa3b, v131
	v_mul_f32_e32 v132, 0xbfb8aa3b, v132
	v_mul_f32_e32 v133, 0xbfb8aa3b, v133
	v_exp_f32_e32 v130, v130
	v_exp_f32_e32 v131, v131
	v_exp_f32_e32 v132, v132
	v_exp_f32_e32 v133, v133
	v_add_f32_e32 v130, 1.0, v130
	v_add_f32_e32 v131, 1.0, v131
	v_add_f32_e32 v132, 1.0, v132
	v_add_f32_e32 v133, 1.0, v133
	v_rcp_f32_e32 v130, v130
	v_rcp_f32_e32 v131, v131
	v_rcp_f32_e32 v132, v132
	v_rcp_f32_e32 v133, v133
	s_nop 0
	v_cvt_pk_bf16_f32 v110, v130, v131
	v_cvt_pk_bf16_f32 v111, v132, v133
	ds_write_b64 v136, v[110:111] offset:2048
	v_add_f32_e32 v130, v106, v164
	v_add_f32_e32 v131, v107, v165
	v_add_f32_e32 v132, v108, v166
	v_add_f32_e32 v133, v109, v167
	v_mul_f32_e32 v130, 0xbfb8aa3b, v130
	v_mul_f32_e32 v131, 0xbfb8aa3b, v131
	v_mul_f32_e32 v132, 0xbfb8aa3b, v132
	v_mul_f32_e32 v133, 0xbfb8aa3b, v133
	v_exp_f32_e32 v130, v130
	v_exp_f32_e32 v131, v131
	v_exp_f32_e32 v132, v132
	v_exp_f32_e32 v133, v133
	v_add_f32_e32 v130, 1.0, v130
	v_add_f32_e32 v131, 1.0, v131
	v_add_f32_e32 v132, 1.0, v132
	v_add_f32_e32 v133, 1.0, v133
	v_rcp_f32_e32 v130, v130
	v_rcp_f32_e32 v131, v131
	v_rcp_f32_e32 v132, v132
	v_rcp_f32_e32 v133, v133
	s_nop 0
	v_cvt_pk_bf16_f32 v106, v130, v131
	v_cvt_pk_bf16_f32 v107, v132, v133
	ds_write_b64 v137, v[106:107] offset:2048
	v_add_f32_e32 v130, v102, v168
	v_add_f32_e32 v131, v103, v169
	v_add_f32_e32 v132, v104, v170
	v_add_f32_e32 v133, v105, v171
	v_mul_f32_e32 v130, 0xbfb8aa3b, v130
	v_mul_f32_e32 v131, 0xbfb8aa3b, v131
	v_mul_f32_e32 v132, 0xbfb8aa3b, v132
	v_mul_f32_e32 v133, 0xbfb8aa3b, v133
	v_exp_f32_e32 v130, v130
	v_exp_f32_e32 v131, v131
	v_exp_f32_e32 v132, v132
	v_exp_f32_e32 v133, v133
	v_add_f32_e32 v130, 1.0, v130
	v_add_f32_e32 v131, 1.0, v131
	v_add_f32_e32 v132, 1.0, v132
	v_add_f32_e32 v133, 1.0, v133
	v_rcp_f32_e32 v130, v130
	v_rcp_f32_e32 v131, v131
	v_rcp_f32_e32 v132, v132
	v_rcp_f32_e32 v133, v133
	s_nop 0
	v_cvt_pk_bf16_f32 v102, v130, v131
	v_cvt_pk_bf16_f32 v103, v132, v133
	ds_write_b64 v138, v[102:103] offset:2048
	v_add_f32_e32 v130, v98, v172
	v_add_f32_e32 v131, v99, v173
	v_add_f32_e32 v132, v100, v174
	v_add_f32_e32 v133, v101, v175
	v_mul_f32_e32 v130, 0xbfb8aa3b, v130
	v_mul_f32_e32 v131, 0xbfb8aa3b, v131
	v_mul_f32_e32 v132, 0xbfb8aa3b, v132
	v_mul_f32_e32 v133, 0xbfb8aa3b, v133
	v_exp_f32_e32 v130, v130
	v_exp_f32_e32 v131, v131
	v_exp_f32_e32 v132, v132
	v_exp_f32_e32 v133, v133
	v_add_f32_e32 v130, 1.0, v130
; __device__ __forceinline__ float siluf(float v) { return v * __builtin_amdgcn_rcpf(1.f + __builtin_amdgcn_exp2f(-1.4426950408889634f * v)); }
; __device__ __forceinline__ float sigmf(float v) { return __builtin_amdgcn_rcpf(1.f + __builtin_amdgcn_exp2f(-1.4426950408889634f * v)); }
; #define G1_STG(mi_, ni_, v_) do { const int r_ = (mi_) * 16 + idx; const f32x4 t_ = (v_); u32x2 pk_; pk_.x = pk2(t_.x, t_.y); pk_.y = pk2(t_.z, t_.w); \
;         *(u32x2*)(wl + r_ * 128 + ((((ni_) * 2 + (kq >> 1)) ^ (r_ & 7)) * 16) + (kq & 1) * 8) = pk_; } while (0)
; __device__ void gemm1_phase(const Params& p, int l, int hb, unsigned char* smem) {
;     ...
;             for (int mi = 0; mi < 8; ++mi) {
; #pragma unroll
;                 for (int ni = 0; ni < 4; ++ni) {
;                     f32x4 v = acc[mi][ni];
;                     if (mode == 1) { v.x = siluf(v.x); v.y = siluf(v.y); v.z = siluf(v.z); v.w = siluf(v.w); }
;                     else if (mode == 2) { const f32x4 bb = *(const f32x4*)(bg + ni * 16); v.x = sigmf(v.x + bb.x); v.y = sigmf(v.y + bb.y); v.z = sigmf(v.z + bb.z); v.w = sigmf(v.w + bb.w); }
;                     G1_STG(mi, ni, v);
;     ...
;         if (dbase) {
;             const int ch = lane & 7;
; #pragma unroll
;             for (int j = 0; j < 16; ++j) {
;                 const int rl = 8 * j + (lane >> 3), row = m0 + wm * 128 + rl;
;                 const u32x4 v = *(const u32x4*)(wl + rl * 128 + ((ch ^ (rl & 7)) * 16));
;                 size_t drow = (size_t)row;
;                 if (dsh >= 0) { const int bl = row >> 13, tt = row & (SEQ - 1); drow = (size_t)(bl * 3 + dg) * SEQ + (size_t)((tt & ((1 << dsh) - 1)) * (SEQ >> dsh) + (tt >> dsh)); }
;                 *(u32x4*)(dbase + drow * dpitch + dc0 + ch * 8) = v;
;             }
	v_add_f32_e32 v131, 1.0, v131
	v_add_f32_e32 v132, 1.0, v132
	v_add_f32_e32 v133, 1.0, v133
	v_rcp_f32_e32 v130, v130
	v_rcp_f32_e32 v131, v131
	v_rcp_f32_e32 v132, v132
	v_rcp_f32_e32 v133, v133
	s_nop 0
	v_cvt_pk_bf16_f32 v98, v130, v131
	v_cvt_pk_bf16_f32 v99, v132, v133
	ds_write_b64 v139, v[98:99] offset:2048
	v_add_f32_e32 v130, v94, v160
	v_add_f32_e32 v131, v95, v161
	v_add_f32_e32 v132, v96, v162
	v_add_f32_e32 v133, v97, v163
	v_mul_f32_e32 v130, 0xbfb8aa3b, v130
	v_mul_f32_e32 v131, 0xbfb8aa3b, v131
	v_mul_f32_e32 v132, 0xbfb8aa3b, v132
	v_mul_f32_e32 v133, 0xbfb8aa3b, v133
	v_exp_f32_e32 v130, v130
	v_exp_f32_e32 v131, v131
	v_exp_f32_e32 v132, v132
	v_exp_f32_e32 v133, v133
	v_add_f32_e32 v130, 1.0, v130
	v_add_f32_e32 v131, 1.0, v131
	v_add_f32_e32 v132, 1.0, v132
	v_add_f32_e32 v133, 1.0, v133
	v_rcp_f32_e32 v130, v130
	v_rcp_f32_e32 v131, v131
	v_rcp_f32_e32 v132, v132
	v_rcp_f32_e32 v133, v133
	s_nop 0
	v_cvt_pk_bf16_f32 v94, v130, v131
	v_cvt_pk_bf16_f32 v95, v132, v133
	ds_write_b64 v136, v[94:95] offset:4096
	v_add_f32_e32 v130, v90, v164
	v_add_f32_e32 v131, v91, v165
	v_add_f32_e32 v132, v92, v166
	v_add_f32_e32 v133, v93, v167
	v_mul_f32_e32 v130, 0xbfb8aa3b, v130
	v_mul_f32_e32 v131, 0xbfb8aa3b, v131
	v_mul_f32_e32 v132, 0xbfb8aa3b, v132
	v_mul_f32_e32 v133, 0xbfb8aa3b, v133
	v_exp_f32_e32 v130, v130
	v_exp_f32_e32 v131, v131
	v_exp_f32_e32 v132, v132
	v_exp_f32_e32 v133, v133
	v_add_f32_e32 v130, 1.0, v130
	v_add_f32_e32 v131, 1.0, v131
	v_add_f32_e32 v132, 1.0, v132
	v_add_f32_e32 v133, 1.0, v133
	v_rcp_f32_e32 v130, v130
	v_rcp_f32_e32 v131, v131
	v_rcp_f32_e32 v132, v132
	v_rcp_f32_e32 v133, v133
	s_nop 0
	v_cvt_pk_bf16_f32 v90, v130, v131
	v_cvt_pk_bf16_f32 v91, v132, v133
	ds_write_b64 v137, v[90:91] offset:4096
	v_add_f32_e32 v130, v86, v168
	v_add_f32_e32 v131, v87, v169
	v_add_f32_e32 v132, v88, v170
	v_add_f32_e32 v133, v89, v171
	v_mul_f32_e32 v130, 0xbfb8aa3b, v130
	v_mul_f32_e32 v131, 0xbfb8aa3b, v131
	v_mul_f32_e32 v132, 0xbfb8aa3b, v132
	v_mul_f32_e32 v133, 0xbfb8aa3b, v133
	v_exp_f32_e32 v130, v130
	v_exp_f32_e32 v131, v131
	v_exp_f32_e32 v132, v132
	v_exp_f32_e32 v133, v133
	v_add_f32_e32 v130, 1.0, v130
	v_add_f32_e32 v131, 1.0, v131
	v_add_f32_e32 v132, 1.0, v132
	v_add_f32_e32 v133, 1.0, v133
	v_rcp_f32_e32 v130, v130
	v_rcp_f32_e32 v131, v131
	v_rcp_f32_e32 v132, v132
	v_rcp_f32_e32 v133, v133
	s_nop 0
	v_cvt_pk_bf16_f32 v86, v130, v131
	v_cvt_pk_bf16_f32 v87, v132, v133
	ds_write_b64 v138, v[86:87] offset:4096
	v_add_f32_e32 v130, v82, v172
	v_add_f32_e32 v131, v83, v173
	v_add_f32_e32 v132, v84, v174
	v_add_f32_e32 v133, v85, v175
	v_mul_f32_e32 v130, 0xbfb8aa3b, v130
	v_mul_f32_e32 v131, 0xbfb8aa3b, v131
	v_mul_f32_e32 v132, 0xbfb8aa3b, v132
	v_mul_f32_e32 v133, 0xbfb8aa3b, v133
	v_exp_f32_e32 v130, v130
	v_exp_f32_e32 v131, v131
	v_exp_f32_e32 v132, v132
	v_exp_f32_e32 v133, v133
	v_add_f32_e32 v130, 1.0, v130
	v_add_f32_e32 v131, 1.0, v131
	v_add_f32_e32 v132, 1.0, v132
	v_add_f32_e32 v133, 1.0, v133
	v_rcp_f32_e32 v130, v130
	v_rcp_f32_e32 v131, v131
	v_rcp_f32_e32 v132, v132
	v_rcp_f32_e32 v133, v133
	s_nop 0
	v_cvt_pk_bf16_f32 v82, v130, v131
	v_cvt_pk_bf16_f32 v83, v132, v133
	ds_write_b64 v139, v[82:83] offset:4096
	v_add_f32_e32 v130, v76, v160
	v_add_f32_e32 v131, v77, v161
	v_add_f32_e32 v132, v78, v162
	v_add_f32_e32 v133, v79, v163
	v_mul_f32_e32 v130, 0xbfb8aa3b, v130
	v_mul_f32_e32 v131, 0xbfb8aa3b, v131
	v_mul_f32_e32 v132, 0xbfb8aa3b, v132
	v_mul_f32_e32 v133, 0xbfb8aa3b, v133
	v_exp_f32_e32 v130, v130
	v_exp_f32_e32 v131, v131
	v_exp_f32_e32 v132, v132
	v_exp_f32_e32 v133, v133
	v_add_f32_e32 v130, 1.0, v130
	v_add_f32_e32 v131, 1.0, v131
	v_add_f32_e32 v132, 1.0, v132
	v_add_f32_e32 v133, 1.0, v133
	v_rcp_f32_e32 v130, v130
	v_rcp_f32_e32 v131, v131
	v_rcp_f32_e32 v132, v132
	v_rcp_f32_e32 v133, v133
	s_nop 0
	v_cvt_pk_bf16_f32 v76, v130, v131
	v_cvt_pk_bf16_f32 v77, v132, v133
	ds_write_b64 v136, v[76:77] offset:6144
	v_add_f32_e32 v130, v72, v164
	v_add_f32_e32 v131, v73, v165
	v_add_f32_e32 v132, v74, v166
	v_add_f32_e32 v133, v75, v167
	v_mul_f32_e32 v130, 0xbfb8aa3b, v130
	v_mul_f32_e32 v131, 0xbfb8aa3b, v131
	v_mul_f32_e32 v132, 0xbfb8aa3b, v132
	v_mul_f32_e32 v133, 0xbfb8aa3b, v133
	v_exp_f32_e32 v130, v130
	v_exp_f32_e32 v131, v131
	v_exp_f32_e32 v132, v132
	v_exp_f32_e32 v133, v133
	v_add_f32_e32 v130, 1.0, v130
	v_add_f32_e32 v131, 1.0, v131
	v_add_f32_e32 v132, 1.0, v132
	v_add_f32_e32 v133, 1.0, v133
	v_rcp_f32_e32 v130, v130
	v_rcp_f32_e32 v131, v131
	v_rcp_f32_e32 v132, v132
	v_rcp_f32_e32 v133, v133
	s_nop 0
	v_cvt_pk_bf16_f32 v72, v130, v131
	v_cvt_pk_bf16_f32 v73, v132, v133
	ds_write_b64 v137, v[72:73] offset:6144
	v_add_f32_e32 v130, v68, v168
	v_add_f32_e32 v131, v69, v169
	v_add_f32_e32 v132, v70, v170
	v_add_f32_e32 v133, v71, v171
	v_mul_f32_e32 v130, 0xbfb8aa3b, v130
	v_mul_f32_e32 v131, 0xbfb8aa3b, v131
	v_mul_f32_e32 v132, 0xbfb8aa3b, v132
	v_mul_f32_e32 v133, 0xbfb8aa3b, v133
	v_exp_f32_e32 v130, v130
	v_exp_f32_e32 v131, v131
	v_exp_f32_e32 v132, v132
	v_exp_f32_e32 v133, v133
	v_add_f32_e32 v130, 1.0, v130
	v_add_f32_e32 v131, 1.0, v131
	v_add_f32_e32 v132, 1.0, v132
	v_add_f32_e32 v133, 1.0, v133
	v_rcp_f32_e32 v130, v130
	v_rcp_f32_e32 v131, v131
	v_rcp_f32_e32 v132, v132
	v_rcp_f32_e32 v133, v133
	s_nop 0
	v_cvt_pk_bf16_f32 v68, v130, v131
	v_cvt_pk_bf16_f32 v69, v132, v133
	ds_write_b64 v138, v[68:69] offset:6144
	v_add_f32_e32 v130, v64, v172
	v_add_f32_e32 v131, v65, v173
	v_add_f32_e32 v132, v66, v174
	v_add_f32_e32 v133, v67, v175
	v_mul_f32_e32 v130, 0xbfb8aa3b, v130
	v_mul_f32_e32 v131, 0xbfb8aa3b, v131
	v_mul_f32_e32 v132, 0xbfb8aa3b, v132
	v_mul_f32_e32 v133, 0xbfb8aa3b, v133
	v_exp_f32_e32 v130, v130
	v_exp_f32_e32 v131, v131
	v_exp_f32_e32 v132, v132
	v_exp_f32_e32 v133, v133
	v_add_f32_e32 v130, 1.0, v130
	v_add_f32_e32 v131, 1.0, v131
	v_add_f32_e32 v132, 1.0, v132
	v_add_f32_e32 v133, 1.0, v133
	v_rcp_f32_e32 v130, v130
	v_rcp_f32_e32 v131, v131
	v_rcp_f32_e32 v132, v132
	v_rcp_f32_e32 v133, v133
	s_nop 0
	v_cvt_pk_bf16_f32 v64, v130, v131
	v_cvt_pk_bf16_f32 v65, v132, v133
	ds_write_b64 v139, v[64:65] offset:6144
	ds_read_b128 v[98:101], v144
	ds_read_b128 v[102:105], v144 offset:1024
	ds_read_b128 v[106:109], v144 offset:2048
	ds_read_b128 v[110:113], v144 offset:3072
	ds_read_b128 v[114:117], v144 offset:4096
	ds_read_b128 v[118:121], v144 offset:5120
	ds_read_b128 v[122:125], v144 offset:6144
	ds_read_b128 v[126:129], v144 offset:7168
	s_waitcnt lgkmcnt(7)
; __device__ __forceinline__ float siluf(float v) { return v * __builtin_amdgcn_rcpf(1.f + __builtin_amdgcn_exp2f(-1.4426950408889634f * v)); }
; __device__ __forceinline__ float sigmf(float v) { return __builtin_amdgcn_rcpf(1.f + __builtin_amdgcn_exp2f(-1.4426950408889634f * v)); }
; #define G1_STG(mi_, ni_, v_) do { const int r_ = (mi_) * 16 + idx; const f32x4 t_ = (v_); u32x2 pk_; pk_.x = pk2(t_.x, t_.y); pk_.y = pk2(t_.z, t_.w); \
;         *(u32x2*)(wl + r_ * 128 + ((((ni_) * 2 + (kq >> 1)) ^ (r_ & 7)) * 16) + (kq & 1) * 8) = pk_; } while (0)
; __device__ void gemm1_phase(const Params& p, int l, int hb, unsigned char* smem) {
;     ...
;             for (int mi = 0; mi < 8; ++mi) {
; #pragma unroll
;                 for (int ni = 0; ni < 4; ++ni) {
;                     f32x4 v = acc[mi][ni];
;                     if (mode == 1) { v.x = siluf(v.x); v.y = siluf(v.y); v.z = siluf(v.z); v.w = siluf(v.w); }
;                     else if (mode == 2) { const f32x4 bb = *(const f32x4*)(bg + ni * 16); v.x = sigmf(v.x + bb.x); v.y = sigmf(v.y + bb.y); v.z = sigmf(v.z + bb.z); v.w = sigmf(v.w + bb.w); }
;                     G1_STG(mi, ni, v);
;     ...
;         if (dbase) {
;             const int ch = lane & 7;
; #pragma unroll
;             for (int j = 0; j < 16; ++j) {
;                 const int rl = 8 * j + (lane >> 3), row = m0 + wm * 128 + rl;
;                 const u32x4 v = *(const u32x4*)(wl + rl * 128 + ((ch ^ (rl & 7)) * 16));
;                 size_t drow = (size_t)row;
;                 if (dsh >= 0) { const int bl = row >> 13, tt = row & (SEQ - 1); drow = (size_t)(bl * 3 + dg) * SEQ + (size_t)((tt & ((1 << dsh) - 1)) * (SEQ >> dsh) + (tt >> dsh)); }
;                 *(u32x4*)(dbase + drow * dpitch + dc0 + ch * 8) = v;
;             }
	global_store_dwordx4 v145, v[98:101], s[90:91]
	v_add_u32_e32 v145, s100, v145
	s_waitcnt lgkmcnt(6)
	global_store_dwordx4 v145, v[102:105], s[90:91]
	v_add_u32_e32 v145, s100, v145
	s_waitcnt lgkmcnt(5)
	global_store_dwordx4 v145, v[106:109], s[90:91]
	v_add_u32_e32 v145, s100, v145
	s_waitcnt lgkmcnt(4)
	global_store_dwordx4 v145, v[110:113], s[90:91]
	v_add_u32_e32 v145, s100, v145
	s_waitcnt lgkmcnt(3)
	global_store_dwordx4 v145, v[114:117], s[90:91]
	v_add_u32_e32 v145, s100, v145
	s_waitcnt lgkmcnt(2)
	global_store_dwordx4 v145, v[118:121], s[90:91]
	v_add_u32_e32 v145, s100, v145
	s_waitcnt lgkmcnt(1)
	global_store_dwordx4 v145, v[122:125], s[90:91]
	v_add_u32_e32 v145, s100, v145
	s_waitcnt lgkmcnt(0)
	global_store_dwordx4 v145, v[126:129], s[90:91]
	v_add_u32_e32 v145, s100, v145
	v_add_f32_e32 v130, v60, v160
	v_add_f32_e32 v131, v61, v161
	v_add_f32_e32 v132, v62, v162
	v_add_f32_e32 v133, v63, v163
	v_mul_f32_e32 v130, 0xbfb8aa3b, v130
	v_mul_f32_e32 v131, 0xbfb8aa3b, v131
	v_mul_f32_e32 v132, 0xbfb8aa3b, v132
	v_mul_f32_e32 v133, 0xbfb8aa3b, v133
	v_exp_f32_e32 v130, v130
	v_exp_f32_e32 v131, v131
	v_exp_f32_e32 v132, v132
	v_exp_f32_e32 v133, v133
	v_add_f32_e32 v130, 1.0, v130
	v_add_f32_e32 v131, 1.0, v131
	v_add_f32_e32 v132, 1.0, v132
	v_add_f32_e32 v133, 1.0, v133
	v_rcp_f32_e32 v130, v130
	v_rcp_f32_e32 v131, v131
	v_rcp_f32_e32 v132, v132
	v_rcp_f32_e32 v133, v133
	s_nop 0
	v_cvt_pk_bf16_f32 v60, v130, v131
	v_cvt_pk_bf16_f32 v61, v132, v133
	ds_write_b64 v136, v[60:61]
	v_add_f32_e32 v130, v56, v164
	v_add_f32_e32 v131, v57, v165
	v_add_f32_e32 v132, v58, v166
	v_add_f32_e32 v133, v59, v167
	v_mul_f32_e32 v130, 0xbfb8aa3b, v130
	v_mul_f32_e32 v131, 0xbfb8aa3b, v131
	v_mul_f32_e32 v132, 0xbfb8aa3b, v132
	v_mul_f32_e32 v133, 0xbfb8aa3b, v133
	v_exp_f32_e32 v130, v130
	v_exp_f32_e32 v131, v131
	v_exp_f32_e32 v132, v132
	v_exp_f32_e32 v133, v133
	v_add_f32_e32 v130, 1.0, v130
	v_add_f32_e32 v131, 1.0, v131
	v_add_f32_e32 v132, 1.0, v132
	v_add_f32_e32 v133, 1.0, v133
	v_rcp_f32_e32 v130, v130
	v_rcp_f32_e32 v131, v131
	v_rcp_f32_e32 v132, v132
	v_rcp_f32_e32 v133, v133
	s_nop 0
	v_cvt_pk_bf16_f32 v56, v130, v131
	v_cvt_pk_bf16_f32 v57, v132, v133
	ds_write_b64 v137, v[56:57]
	v_add_f32_e32 v130, v52, v168
	v_add_f32_e32 v131, v53, v169
	v_add_f32_e32 v132, v54, v170
	v_add_f32_e32 v133, v55, v171
	v_mul_f32_e32 v130, 0xbfb8aa3b, v130
	v_mul_f32_e32 v131, 0xbfb8aa3b, v131
	v_mul_f32_e32 v132, 0xbfb8aa3b, v132
	v_mul_f32_e32 v133, 0xbfb8aa3b, v133
	v_exp_f32_e32 v130, v130
	v_exp_f32_e32 v131, v131
	v_exp_f32_e32 v132, v132
	v_exp_f32_e32 v133, v133
	v_add_f32_e32 v130, 1.0, v130
	v_add_f32_e32 v131, 1.0, v131
	v_add_f32_e32 v132, 1.0, v132
	v_add_f32_e32 v133, 1.0, v133
	v_rcp_f32_e32 v130, v130
	v_rcp_f32_e32 v131, v131
	v_rcp_f32_e32 v132, v132
	v_rcp_f32_e32 v133, v133
	s_nop 0
	v_cvt_pk_bf16_f32 v52, v130, v131
	v_cvt_pk_bf16_f32 v53, v132, v133
	ds_write_b64 v138, v[52:53]
	v_add_f32_e32 v130, v48, v172
	v_add_f32_e32 v131, v49, v173
	v_add_f32_e32 v132, v50, v174
	v_add_f32_e32 v133, v51, v175
	v_mul_f32_e32 v130, 0xbfb8aa3b, v130
	v_mul_f32_e32 v131, 0xbfb8aa3b, v131
	v_mul_f32_e32 v132, 0xbfb8aa3b, v132
	v_mul_f32_e32 v133, 0xbfb8aa3b, v133
	v_exp_f32_e32 v130, v130
	v_exp_f32_e32 v131, v131
	v_exp_f32_e32 v132, v132
	v_exp_f32_e32 v133, v133
	v_add_f32_e32 v130, 1.0, v130
	v_add_f32_e32 v131, 1.0, v131
	v_add_f32_e32 v132, 1.0, v132
	v_add_f32_e32 v133, 1.0, v133
	v_rcp_f32_e32 v130, v130
	v_rcp_f32_e32 v131, v131
	v_rcp_f32_e32 v132, v132
	v_rcp_f32_e32 v133, v133
	s_nop 0
	v_cvt_pk_bf16_f32 v48, v130, v131
	v_cvt_pk_bf16_f32 v49, v132, v133
	ds_write_b64 v139, v[48:49]
	v_add_f32_e32 v130, v44, v160
	v_add_f32_e32 v131, v45, v161
	v_add_f32_e32 v132, v46, v162
	v_add_f32_e32 v133, v47, v163
	v_mul_f32_e32 v130, 0xbfb8aa3b, v130
	v_mul_f32_e32 v131, 0xbfb8aa3b, v131
	v_mul_f32_e32 v132, 0xbfb8aa3b, v132
	v_mul_f32_e32 v133, 0xbfb8aa3b, v133
	v_exp_f32_e32 v130, v130
	v_exp_f32_e32 v131, v131
	v_exp_f32_e32 v132, v132
	v_exp_f32_e32 v133, v133
	v_add_f32_e32 v130, 1.0, v130
	v_add_f32_e32 v131, 1.0, v131
	v_add_f32_e32 v132, 1.0, v132
	v_add_f32_e32 v133, 1.0, v133
	v_rcp_f32_e32 v130, v130
	v_rcp_f32_e32 v131, v131
	v_rcp_f32_e32 v132, v132
	v_rcp_f32_e32 v133, v133
	s_nop 0
	v_cvt_pk_bf16_f32 v44, v130, v131
	v_cvt_pk_bf16_f32 v45, v132, v133
	ds_write_b64 v136, v[44:45] offset:2048
	v_add_f32_e32 v130, v40, v164
	v_add_f32_e32 v131, v41, v165
	v_add_f32_e32 v132, v42, v166
	v_add_f32_e32 v133, v43, v167
	v_mul_f32_e32 v130, 0xbfb8aa3b, v130
	v_mul_f32_e32 v131, 0xbfb8aa3b, v131
	v_mul_f32_e32 v132, 0xbfb8aa3b, v132
	v_mul_f32_e32 v133, 0xbfb8aa3b, v133
	v_exp_f32_e32 v130, v130
	v_exp_f32_e32 v131, v131
	v_exp_f32_e32 v132, v132
	v_exp_f32_e32 v133, v133
	v_add_f32_e32 v130, 1.0, v130
	v_add_f32_e32 v131, 1.0, v131
	v_add_f32_e32 v132, 1.0, v132
	v_add_f32_e32 v133, 1.0, v133
	v_rcp_f32_e32 v130, v130
	v_rcp_f32_e32 v131, v131
	v_rcp_f32_e32 v132, v132
	v_rcp_f32_e32 v133, v133
	s_nop 0
	v_cvt_pk_bf16_f32 v40, v130, v131
	v_cvt_pk_bf16_f32 v41, v132, v133
	ds_write_b64 v137, v[40:41] offset:2048
	v_add_f32_e32 v130, v36, v168
	v_add_f32_e32 v131, v37, v169
	v_add_f32_e32 v132, v38, v170
	v_add_f32_e32 v133, v39, v171
	v_mul_f32_e32 v130, 0xbfb8aa3b, v130
	v_mul_f32_e32 v131, 0xbfb8aa3b, v131
	v_mul_f32_e32 v132, 0xbfb8aa3b, v132
	v_mul_f32_e32 v133, 0xbfb8aa3b, v133
	v_exp_f32_e32 v130, v130
	v_exp_f32_e32 v131, v131
	v_exp_f32_e32 v132, v132
	v_exp_f32_e32 v133, v133
	v_add_f32_e32 v130, 1.0, v130
	v_add_f32_e32 v131, 1.0, v131
	v_add_f32_e32 v132, 1.0, v132
	v_add_f32_e32 v133, 1.0, v133
	v_rcp_f32_e32 v130, v130
; __device__ __forceinline__ float siluf(float v) { return v * __builtin_amdgcn_rcpf(1.f + __builtin_amdgcn_exp2f(-1.4426950408889634f * v)); }
; __device__ __forceinline__ float sigmf(float v) { return __builtin_amdgcn_rcpf(1.f + __builtin_amdgcn_exp2f(-1.4426950408889634f * v)); }
; #define G1_STG(mi_, ni_, v_) do { const int r_ = (mi_) * 16 + idx; const f32x4 t_ = (v_); u32x2 pk_; pk_.x = pk2(t_.x, t_.y); pk_.y = pk2(t_.z, t_.w); \
;         *(u32x2*)(wl + r_ * 128 + ((((ni_) * 2 + (kq >> 1)) ^ (r_ & 7)) * 16) + (kq & 1) * 8) = pk_; } while (0)
; __device__ void gemm1_phase(const Params& p, int l, int hb, unsigned char* smem) {
;     ...
;             for (int mi = 0; mi < 8; ++mi) {
; #pragma unroll
;                 for (int ni = 0; ni < 4; ++ni) {
;                     f32x4 v = acc[mi][ni];
;                     if (mode == 1) { v.x = siluf(v.x); v.y = siluf(v.y); v.z = siluf(v.z); v.w = siluf(v.w); }
;                     else if (mode == 2) { const f32x4 bb = *(const f32x4*)(bg + ni * 16); v.x = sigmf(v.x + bb.x); v.y = sigmf(v.y + bb.y); v.z = sigmf(v.z + bb.z); v.w = sigmf(v.w + bb.w); }
;                     G1_STG(mi, ni, v);
	v_rcp_f32_e32 v131, v131
	v_rcp_f32_e32 v132, v132
	v_rcp_f32_e32 v133, v133
	s_nop 0
	v_cvt_pk_bf16_f32 v36, v130, v131
	v_cvt_pk_bf16_f32 v37, v132, v133
	ds_write_b64 v138, v[36:37] offset:2048
	v_add_f32_e32 v130, v32, v172
	v_add_f32_e32 v131, v33, v173
	v_add_f32_e32 v132, v34, v174
	v_add_f32_e32 v133, v35, v175
	v_mul_f32_e32 v130, 0xbfb8aa3b, v130
	v_mul_f32_e32 v131, 0xbfb8aa3b, v131
	v_mul_f32_e32 v132, 0xbfb8aa3b, v132
	v_mul_f32_e32 v133, 0xbfb8aa3b, v133
	v_exp_f32_e32 v130, v130
	v_exp_f32_e32 v131, v131
	v_exp_f32_e32 v132, v132
	v_exp_f32_e32 v133, v133
	v_add_f32_e32 v130, 1.0, v130
	v_add_f32_e32 v131, 1.0, v131
	v_add_f32_e32 v132, 1.0, v132
	v_add_f32_e32 v133, 1.0, v133
	v_rcp_f32_e32 v130, v130
	v_rcp_f32_e32 v131, v131
	v_rcp_f32_e32 v132, v132
	v_rcp_f32_e32 v133, v133
	s_nop 0
	v_cvt_pk_bf16_f32 v32, v130, v131
	v_cvt_pk_bf16_f32 v33, v132, v133
	ds_write_b64 v139, v[32:33] offset:2048
	v_add_f32_e32 v130, v28, v160
	v_add_f32_e32 v131, v29, v161
	v_add_f32_e32 v132, v30, v162
	v_add_f32_e32 v133, v31, v163
	v_mul_f32_e32 v130, 0xbfb8aa3b, v130
	v_mul_f32_e32 v131, 0xbfb8aa3b, v131
	v_mul_f32_e32 v132, 0xbfb8aa3b, v132
	v_mul_f32_e32 v133, 0xbfb8aa3b, v133
	v_exp_f32_e32 v130, v130
	v_exp_f32_e32 v131, v131
	v_exp_f32_e32 v132, v132
	v_exp_f32_e32 v133, v133
	v_add_f32_e32 v130, 1.0, v130
	v_add_f32_e32 v131, 1.0, v131
	v_add_f32_e32 v132, 1.0, v132
	v_add_f32_e32 v133, 1.0, v133
	v_rcp_f32_e32 v130, v130
	v_rcp_f32_e32 v131, v131
	v_rcp_f32_e32 v132, v132
	v_rcp_f32_e32 v133, v133
	s_nop 0
	v_cvt_pk_bf16_f32 v28, v130, v131
	v_cvt_pk_bf16_f32 v29, v132, v133
	ds_write_b64 v136, v[28:29] offset:4096
	v_add_f32_e32 v130, v24, v164
	v_add_f32_e32 v131, v25, v165
	v_add_f32_e32 v132, v26, v166
	v_add_f32_e32 v133, v27, v167
	v_mul_f32_e32 v130, 0xbfb8aa3b, v130
	v_mul_f32_e32 v131, 0xbfb8aa3b, v131
	v_mul_f32_e32 v132, 0xbfb8aa3b, v132
	v_mul_f32_e32 v133, 0xbfb8aa3b, v133
	v_exp_f32_e32 v130, v130
	v_exp_f32_e32 v131, v131
	v_exp_f32_e32 v132, v132
	v_exp_f32_e32 v133, v133
	v_add_f32_e32 v130, 1.0, v130
	v_add_f32_e32 v131, 1.0, v131
	v_add_f32_e32 v132, 1.0, v132
	v_add_f32_e32 v133, 1.0, v133
	v_rcp_f32_e32 v130, v130
	v_rcp_f32_e32 v131, v131
	v_rcp_f32_e32 v132, v132
	v_rcp_f32_e32 v133, v133
	s_nop 0
	v_cvt_pk_bf16_f32 v24, v130, v131
	v_cvt_pk_bf16_f32 v25, v132, v133
	ds_write_b64 v137, v[24:25] offset:4096
	v_add_f32_e32 v130, v20, v168
	v_add_f32_e32 v131, v21, v169
	v_add_f32_e32 v132, v22, v170
	v_add_f32_e32 v133, v23, v171
	v_mul_f32_e32 v130, 0xbfb8aa3b, v130
	v_mul_f32_e32 v131, 0xbfb8aa3b, v131
	v_mul_f32_e32 v132, 0xbfb8aa3b, v132
	v_mul_f32_e32 v133, 0xbfb8aa3b, v133
	v_exp_f32_e32 v130, v130
	v_exp_f32_e32 v131, v131
	v_exp_f32_e32 v132, v132
	v_exp_f32_e32 v133, v133
	v_add_f32_e32 v130, 1.0, v130
	v_add_f32_e32 v131, 1.0, v131
	v_add_f32_e32 v132, 1.0, v132
	v_add_f32_e32 v133, 1.0, v133
	v_rcp_f32_e32 v130, v130
	v_rcp_f32_e32 v131, v131
	v_rcp_f32_e32 v132, v132
	v_rcp_f32_e32 v133, v133
	s_nop 0
	v_cvt_pk_bf16_f32 v20, v130, v131
	v_cvt_pk_bf16_f32 v21, v132, v133
	ds_write_b64 v138, v[20:21] offset:4096
	v_add_f32_e32 v130, v16, v172
	v_add_f32_e32 v131, v17, v173
	v_add_f32_e32 v132, v18, v174
	v_add_f32_e32 v133, v19, v175
	v_mul_f32_e32 v130, 0xbfb8aa3b, v130
	v_mul_f32_e32 v131, 0xbfb8aa3b, v131
	v_mul_f32_e32 v132, 0xbfb8aa3b, v132
	v_mul_f32_e32 v133, 0xbfb8aa3b, v133
	v_exp_f32_e32 v130, v130
	v_exp_f32_e32 v131, v131
	v_exp_f32_e32 v132, v132
	v_exp_f32_e32 v133, v133
	v_add_f32_e32 v130, 1.0, v130
	v_add_f32_e32 v131, 1.0, v131
	v_add_f32_e32 v132, 1.0, v132
	v_add_f32_e32 v133, 1.0, v133
	v_rcp_f32_e32 v130, v130
	v_rcp_f32_e32 v131, v131
	v_rcp_f32_e32 v132, v132
	v_rcp_f32_e32 v133, v133
	s_nop 0
	v_cvt_pk_bf16_f32 v16, v130, v131
	v_cvt_pk_bf16_f32 v17, v132, v133
	ds_write_b64 v139, v[16:17] offset:4096
	v_add_f32_e32 v130, v12, v160
	v_add_f32_e32 v131, v13, v161
	v_add_f32_e32 v132, v14, v162
; __device__ __forceinline__ float siluf(float v) { return v * __builtin_amdgcn_rcpf(1.f + __builtin_amdgcn_exp2f(-1.4426950408889634f * v)); }
; __device__ __forceinline__ float sigmf(float v) { return __builtin_amdgcn_rcpf(1.f + __builtin_amdgcn_exp2f(-1.4426950408889634f * v)); }
; #define G1_STG(mi_, ni_, v_) do { const int r_ = (mi_) * 16 + idx; const f32x4 t_ = (v_); u32x2 pk_; pk_.x = pk2(t_.x, t_.y); pk_.y = pk2(t_.z, t_.w); \
;         *(u32x2*)(wl + r_ * 128 + ((((ni_) * 2 + (kq >> 1)) ^ (r_ & 7)) * 16) + (kq & 1) * 8) = pk_; } while (0)
; __device__ void gemm1_phase(const Params& p, int l, int hb, unsigned char* smem) {
;     ...
;             for (int mi = 0; mi < 8; ++mi) {
; #pragma unroll
;                 for (int ni = 0; ni < 4; ++ni) {
;                     f32x4 v = acc[mi][ni];
;                     if (mode == 1) { v.x = siluf(v.x); v.y = siluf(v.y); v.z = siluf(v.z); v.w = siluf(v.w); }
;                     else if (mode == 2) { const f32x4 bb = *(const f32x4*)(bg + ni * 16); v.x = sigmf(v.x + bb.x); v.y = sigmf(v.y + bb.y); v.z = sigmf(v.z + bb.z); v.w = sigmf(v.w + bb.w); }
;                     G1_STG(mi, ni, v);
;     ...
;         if (dbase) {
;             const int ch = lane & 7;
; #pragma unroll
;             for (int j = 0; j < 16; ++j) {
;                 const int rl = 8 * j + (lane >> 3), row = m0 + wm * 128 + rl;
;                 const u32x4 v = *(const u32x4*)(wl + rl * 128 + ((ch ^ (rl & 7)) * 16));
;                 size_t drow = (size_t)row;
;                 if (dsh >= 0) { const int bl = row >> 13, tt = row & (SEQ - 1); drow = (size_t)(bl * 3 + dg) * SEQ + (size_t)((tt & ((1 << dsh) - 1)) * (SEQ >> dsh) + (tt >> dsh)); }
;                 *(u32x4*)(dbase + drow * dpitch + dc0 + ch * 8) = v;
;             }
	v_add_f32_e32 v133, v15, v163
	v_mul_f32_e32 v130, 0xbfb8aa3b, v130
	v_mul_f32_e32 v131, 0xbfb8aa3b, v131
	v_mul_f32_e32 v132, 0xbfb8aa3b, v132
	v_mul_f32_e32 v133, 0xbfb8aa3b, v133
	v_exp_f32_e32 v130, v130
	v_exp_f32_e32 v131, v131
	v_exp_f32_e32 v132, v132
	v_exp_f32_e32 v133, v133
	v_add_f32_e32 v130, 1.0, v130
	v_add_f32_e32 v131, 1.0, v131
	v_add_f32_e32 v132, 1.0, v132
	v_add_f32_e32 v133, 1.0, v133
	v_rcp_f32_e32 v130, v130
	v_rcp_f32_e32 v131, v131
	v_rcp_f32_e32 v132, v132
	v_rcp_f32_e32 v133, v133
	s_nop 0
	v_cvt_pk_bf16_f32 v12, v130, v131
	v_cvt_pk_bf16_f32 v13, v132, v133
	ds_write_b64 v136, v[12:13] offset:6144
	v_add_f32_e32 v130, v8, v164
	v_add_f32_e32 v131, v9, v165
	v_add_f32_e32 v132, v10, v166
	v_add_f32_e32 v133, v11, v167
	v_mul_f32_e32 v130, 0xbfb8aa3b, v130
	v_mul_f32_e32 v131, 0xbfb8aa3b, v131
	v_mul_f32_e32 v132, 0xbfb8aa3b, v132
	v_mul_f32_e32 v133, 0xbfb8aa3b, v133
	v_exp_f32_e32 v130, v130
	v_exp_f32_e32 v131, v131
	v_exp_f32_e32 v132, v132
	v_exp_f32_e32 v133, v133
	v_add_f32_e32 v130, 1.0, v130
	v_add_f32_e32 v131, 1.0, v131
	v_add_f32_e32 v132, 1.0, v132
	v_add_f32_e32 v133, 1.0, v133
	v_rcp_f32_e32 v130, v130
	v_rcp_f32_e32 v131, v131
	v_rcp_f32_e32 v132, v132
	v_rcp_f32_e32 v133, v133
	s_nop 0
	v_cvt_pk_bf16_f32 v8, v130, v131
	v_cvt_pk_bf16_f32 v9, v132, v133
	ds_write_b64 v137, v[8:9] offset:6144
	v_add_f32_e32 v130, v4, v168
	v_add_f32_e32 v131, v5, v169
	v_add_f32_e32 v132, v6, v170
	v_add_f32_e32 v133, v7, v171
	v_mul_f32_e32 v130, 0xbfb8aa3b, v130
	v_mul_f32_e32 v131, 0xbfb8aa3b, v131
	v_mul_f32_e32 v132, 0xbfb8aa3b, v132
	v_mul_f32_e32 v133, 0xbfb8aa3b, v133
	v_exp_f32_e32 v130, v130
	v_exp_f32_e32 v131, v131
	v_exp_f32_e32 v132, v132
	v_exp_f32_e32 v133, v133
	v_add_f32_e32 v130, 1.0, v130
	v_add_f32_e32 v131, 1.0, v131
	v_add_f32_e32 v132, 1.0, v132
	v_add_f32_e32 v133, 1.0, v133
	v_rcp_f32_e32 v130, v130
	v_rcp_f32_e32 v131, v131
	v_rcp_f32_e32 v132, v132
	v_rcp_f32_e32 v133, v133
	s_nop 0
	v_cvt_pk_bf16_f32 v4, v130, v131
	v_cvt_pk_bf16_f32 v5, v132, v133
	ds_write_b64 v138, v[4:5] offset:6144
	v_add_f32_e32 v130, v0, v172
	v_add_f32_e32 v131, v1, v173
	v_add_f32_e32 v132, v2, v174
	v_add_f32_e32 v133, v3, v175
	v_mul_f32_e32 v130, 0xbfb8aa3b, v130
	v_mul_f32_e32 v131, 0xbfb8aa3b, v131
	v_mul_f32_e32 v132, 0xbfb8aa3b, v132
	v_mul_f32_e32 v133, 0xbfb8aa3b, v133
	v_exp_f32_e32 v130, v130
	v_exp_f32_e32 v131, v131
	v_exp_f32_e32 v132, v132
	v_exp_f32_e32 v133, v133
	v_add_f32_e32 v130, 1.0, v130
	v_add_f32_e32 v131, 1.0, v131
	v_add_f32_e32 v132, 1.0, v132
	v_add_f32_e32 v133, 1.0, v133
	v_rcp_f32_e32 v130, v130
	v_rcp_f32_e32 v131, v131
	v_rcp_f32_e32 v132, v132
	v_rcp_f32_e32 v133, v133
	s_nop 0
	v_cvt_pk_bf16_f32 v0, v130, v131
	v_cvt_pk_bf16_f32 v1, v132, v133
	ds_write_b64 v139, v[0:1] offset:6144
	ds_read_b128 v[0:3], v144
	ds_read_b128 v[4:7], v144 offset:1024
	ds_read_b128 v[8:11], v144 offset:2048
	ds_read_b128 v[12:15], v144 offset:3072
	ds_read_b128 v[16:19], v144 offset:4096
	ds_read_b128 v[20:23], v144 offset:5120
	ds_read_b128 v[24:27], v144 offset:6144
	ds_read_b128 v[28:31], v144 offset:7168
	s_waitcnt lgkmcnt(7)
	global_store_dwordx4 v145, v[0:3], s[90:91]
	v_add_u32_e32 v145, s100, v145
	s_waitcnt lgkmcnt(6)
	global_store_dwordx4 v145, v[4:7], s[90:91]
	v_add_u32_e32 v145, s100, v145
	s_waitcnt lgkmcnt(5)
	global_store_dwordx4 v145, v[8:11], s[90:91]
	v_add_u32_e32 v145, s100, v145
	s_waitcnt lgkmcnt(4)
	global_store_dwordx4 v145, v[12:15], s[90:91]
	v_add_u32_e32 v145, s100, v145
	s_waitcnt lgkmcnt(3)
	global_store_dwordx4 v145, v[16:19], s[90:91]
	v_add_u32_e32 v145, s100, v145
	s_waitcnt lgkmcnt(2)
	global_store_dwordx4 v145, v[20:23], s[90:91]
	v_add_u32_e32 v145, s100, v145
	s_waitcnt lgkmcnt(1)
	global_store_dwordx4 v145, v[24:27], s[90:91]
	v_add_u32_e32 v145, s100, v145
	s_waitcnt lgkmcnt(0)
	global_store_dwordx4 v145, v[28:31], s[90:91]
	v_add_u32_e32 v145, s100, v145
	s_branch .LBB0_253
	s_mov_b64 s[36:37], 0
